# speedup vs baseline: 1.0070x; 1.0070x over previous
; __device__ void phaseA_tile(const Params& p, int l, int mt, int nt, char* smem) {
;     ...
;                     const int b = m0 >> 11, t0 = m0 & 2047;
; #pragma unroll
;                     for (int it = 0; it < 8; ++it) {
;                         const int idx = it * 256 + tid;
;                         const int tg = idx & 15, c = idx >> 4;
;                         float f[8];
; #pragma unroll
;                         for (int e = 0; e < 8; ++e) {
;                             const int rl = tg * 8 + e;
;                             f[e] = *(const float*)(smem + rl * 512 + (((c >> 2) ^ (rl & 31)) << 4) + (c & 3) * 4);
;                         }
;                         *(uint4*)(p.vT + ((size_t)(b * 1024 + c0 + c)) * 2048 + t0 + tg * 8) =
;                             make_uint4(pk2(f[0], f[1]), pk2(f[2], f[3]), pk2(f[4], f[5]), pk2(f[6], f[7]));
;                     }
; __device__ void phaseA(const Params& p, int l, char* smem) {
;     for (int k = 0; k < 49; ++k) {
;         int mt, nt;
;         if (!tile_map(k, NT_IN, mt, nt)) continue;
;         phaseA_tile(p, l, mt, nt, smem);
.LBB0_142:
	v_writelane_b32 v212, s18, 3
	s_xor_b64 s[0:1], s[18:19], -1
	s_mov_b32 s21, s3
	v_writelane_b32 v212, s19, 4
	v_writelane_b32 v212, s0, 5
	v_readlane_b32 s40, v214, 0
	v_readlane_b32 s48, v214, 8
	v_writelane_b32 v212, s1, 6
	v_writelane_b32 v212, s20, 7
	s_lshl_b32 s4, s20, 3
	v_readlane_b32 s49, v214, 9
	v_writelane_b32 v212, s21, 8
	v_writelane_b32 v212, s4, 9
	s_lshl_b32 s4, s20, 8
	v_readlane_b32 s50, v214, 10
	v_readlane_b32 s51, v214, 11
	v_readlane_b32 s52, v214, 12
	v_readlane_b32 s53, v214, 13
	v_readlane_b32 s54, v214, 14
	v_readlane_b32 s55, v214, 15
	s_mov_b64 s[24:25], s[48:49]
	s_lshl_b32 s8, s20, 5
	s_lshl_b32 s58, s20, 4
	s_lshl_b64 s[6:7], s[20:21], 21
	s_lshl_b64 s[0:1], s[20:21], 13
	s_lshl_b32 s2, s20, 11
	v_writelane_b32 v212, s4, 10
	s_lshl_b64 s[4:5], s[20:21], 27
	s_mov_b64 s[26:27], s[50:51]
	s_add_u32 s10, s26, s4
	s_addc_u32 s11, s27, s5
	s_mul_hi_u32 s5, s20, 0xf8080000
	s_mul_i32 s4, s20, 0xf8080000
	s_sub_i32 s5, s5, s20
	s_add_u32 s4, s10, s4
	v_writelane_b32 v212, s4, 11
	v_writelane_b32 v212, s11, 13
	s_addc_u32 s4, s11, s5
	v_readlane_b32 s41, v214, 1
	v_readlane_b32 s42, v214, 2
	v_readlane_b32 s43, v214, 3
	v_readlane_b32 s44, v214, 4
	v_readlane_b32 s45, v214, 5
	v_readlane_b32 s46, v214, 6
	v_readlane_b32 s47, v214, 7
	v_writelane_b32 v212, s4, 15
	s_mov_b32 s4, s8
	s_mov_b32 s9, s3
	s_mov_b64 s[28:29], s[52:53]
	s_mov_b64 s[30:31], s[54:55]
	v_writelane_b32 v212, s4, 17
	v_readlane_b32 s40, v214, 18
	v_readlane_b32 s44, v214, 22
	v_writelane_b32 v212, s5, 18
	s_lshl_b64 s[4:5], s[8:9], 2
	s_mov_b32 s59, s3
	v_readlane_b32 s45, v214, 23
	s_add_u32 s74, s44, s4
	v_readlane_b32 s52, v214, 30
	s_addc_u32 s75, s45, s5
	s_lshl_b64 s[4:5], s[58:59], 2
	v_readlane_b32 s53, v214, 31
	s_add_u32 s78, s52, s4
	v_readlane_b32 s48, v214, 26
	v_readlane_b32 s49, v214, 27
	s_addc_u32 s79, s53, s5
	v_readlane_b32 s4, v213, 20
	v_readlane_b32 s42, v214, 20
	v_readlane_b32 s48, v212, 7
	s_add_u32 s59, s4, s6
	v_readlane_b32 s4, v213, 21
	v_readlane_b32 s43, v214, 21
	v_readlane_b32 s49, v212, 8
	v_writelane_b32 v212, s6, 19
	s_addc_u32 s42, s4, s7
	v_readlane_b32 s4, v213, 22
	v_readlane_b32 s46, v214, 24
	s_add_u32 s43, s4, s0
	v_readlane_b32 s0, v213, 23
	v_readlane_b32 s47, v214, 25
	v_readlane_b32 s54, v214, 32
	s_addc_u32 s46, s0, s1
	s_lshl_b64 s[0:1], s[2:3], 2
	v_readlane_b32 s50, v214, 28
	v_readlane_b32 s55, v214, 33
	s_add_u32 s47, s54, s0
	s_addc_u32 s50, s55, s1
	s_mul_i32 s1, s48, 0x1840000
	v_readlane_b32 s51, v214, 29
	s_mul_hi_u32 s0, s48, 0x1840000
	s_add_u32 s44, s30, s1
	s_mov_b32 s49, s10
	s_addc_u32 s45, s31, s0
	s_mov_b32 s51, s3
	v_readlane_b32 s41, v214, 19
	v_writelane_b32 v212, s7, 20
	s_cmp_lt_u32 s96, 4
	s_cbranch_scc1 .Lstag_skip
	s_sleep 127
	s_sleep 127
	s_sleep 127
.Lstag_skip:
	s_branch .LBB0_148
.LBB0_143:
	v_ashrrev_i32_e32 v11, 6, v70
	s_waitcnt lgkmcnt(1)
	v_lshlrev_b32_e32 v3, 2, v33
	v_lshlrev_b32_e32 v2, 12, v72
	v_and_b32_e32 v34, 12, v3
	v_bitop3_b32 v3, v0, v11, 24 bitop3:0x6c
	v_lshl_add_u32 v3, v3, 4, v2
	v_or_b32_e32 v3, v3, v34
	ds_read_b32 v35, v3
	v_or_b32_e32 v3, 1, v0
	v_lshlrev_b32_e32 v4, 9, v3
	v_bitop3_b32 v5, v3, v11, 25 bitop3:0x6c
	v_lshl_add_u32 v5, v5, 4, v4
	v_or_b32_e32 v5, v5, v34
	ds_read_b32 v36, v5
	v_or_b32_e32 v5, 2, v0
	s_waitcnt lgkmcnt(2)
	v_lshlrev_b32_e32 v6, 9, v5
	v_bitop3_b32 v7, v5, v11, 26 bitop3:0x6c
	v_lshl_add_u32 v7, v7, 4, v6
	v_or_b32_e32 v7, v7, v34
	ds_read_b32 v37, v7
	v_or_b32_e32 v7, 3, v0
	v_lshlrev_b32_e32 v8, 9, v7
	v_bitop3_b32 v9, v7, v11, 27 bitop3:0x6c
	v_lshl_add_u32 v9, v9, 4, v8
	v_or_b32_e32 v9, v9, v34
	ds_read_b32 v38, v9
	v_or_b32_e32 v9, 4, v0
	v_lshlrev_b32_e32 v12, 9, v9
	v_bitop3_b32 v26, v9, v11, 28 bitop3:0x6c
	v_lshl_add_u32 v26, v26, 4, v12
	v_or_b32_e32 v26, v26, v34
	ds_read_b32 v39, v26
	v_or_b32_e32 v26, 5, v0
	v_lshlrev_b32_e32 v27, 9, v26
	v_bitop3_b32 v28, v26, v11, 29 bitop3:0x6c
	v_lshl_add_u32 v28, v28, 4, v27
	v_or_b32_e32 v28, v28, v34
	ds_read_b32 v40, v28
	v_or_b32_e32 v28, 6, v0
	v_lshlrev_b32_e32 v29, 9, v28
	v_bitop3_b32 v30, v28, v11, 30 bitop3:0x6c
	v_lshl_add_u32 v30, v30, 4, v29
	v_or_b32_e32 v30, v30, v34
	ds_read_b32 v41, v30
	v_or_b32_e32 v30, 7, v0
	v_lshlrev_b32_e32 v31, 9, v30
	v_bitop3_b32 v11, v30, v11, 31 bitop3:0x6c
	s_lshl_b32 s1, s52, 6
	v_lshl_add_u32 v11, v11, 4, v31
	s_and_b32 s1, s1, 0xfffffc00
	v_or_b32_e32 v11, v11, v34
	s_add_i32 s6, s0, s1
	ds_read_b32 v11, v11
	s_waitcnt lgkmcnt(6)
	v_cvt_pk_bf16_f32 v34, v35, v36
	s_waitcnt lgkmcnt(4)
	v_cvt_pk_bf16_f32 v35, v37, v38
	v_add_u32_e32 v38, s6, v33
	v_ashrrev_i32_e32 v22, 6, v22
	s_waitcnt lgkmcnt(2)
	v_cvt_pk_bf16_f32 v36, v39, v40
	v_ashrrev_i32_e32 v39, 31, v38
	v_readlane_b32 s8, v214, 50
	v_lshlrev_b32_e32 v33, 2, v32
	v_bitop3_b32 v40, v28, v22, 30 bitop3:0x6c
	s_and_b32 s2, s54, 0x780
	v_lshlrev_b64 v[38:39], 12, v[38:39]
	v_readlane_b32 s14, v214, 56
	v_readlane_b32 s15, v214, 57
	v_and_b32_e32 v33, 12, v33
	v_lshl_add_u32 v40, v40, 4, v29
	v_lshl_add_u64 v[38:39], s[14:15], 0, v[38:39]
	s_lshl_b32 s0, s2, 1
	s_mov_b32 s1, s3
	v_or_b32_e32 v40, v40, v33
	v_lshl_add_u64 v[38:39], v[38:39], 0, s[0:1]
	ds_read_b32 v40, v40
	s_waitcnt lgkmcnt(1)
; __device__ void phaseA_tile(const Params& p, int l, int mt, int nt, char* smem) {
;     ...
;                     const int b = m0 >> 11, t0 = m0 & 2047;
; #pragma unroll
;                     for (int it = 0; it < 8; ++it) {
;                         const int idx = it * 256 + tid;
;                         const int tg = idx & 15, c = idx >> 4;
;                         float f[8];
; #pragma unroll
;                         for (int e = 0; e < 8; ++e) {
;                             const int rl = tg * 8 + e;
;                             f[e] = *(const float*)(smem + rl * 512 + (((c >> 2) ^ (rl & 31)) << 4) + (c & 3) * 4);
;                         }
;                         *(uint4*)(p.vT + ((size_t)(b * 1024 + c0 + c)) * 2048 + t0 + tg * 8) =
;                             make_uint4(pk2(f[0], f[1]), pk2(f[2], f[3]), pk2(f[4], f[5]), pk2(f[6], f[7]));
;                     }
	v_cvt_pk_bf16_f32 v37, v41, v11
	v_mov_b32_e32 v11, v1
	v_lshl_add_u64 v[38:39], v[38:39], 0, v[10:11]
	global_store_dwordx4 v[38:39], v[34:37], off
	v_bitop3_b32 v38, v9, v22, 28 bitop3:0x6c
	v_bitop3_b32 v39, v26, v22, 29 bitop3:0x6c
	v_bitop3_b32 v34, v0, v22, 24 bitop3:0x6c
	v_bitop3_b32 v35, v3, v22, 25 bitop3:0x6c
	v_bitop3_b32 v36, v5, v22, 26 bitop3:0x6c
	v_bitop3_b32 v37, v7, v22, 27 bitop3:0x6c
	v_bitop3_b32 v22, v30, v22, 31 bitop3:0x6c
	v_lshl_add_u32 v34, v34, 4, v2
	v_lshl_add_u32 v35, v35, 4, v4
	v_lshl_add_u32 v36, v36, 4, v6
	v_lshl_add_u32 v37, v37, 4, v8
	v_lshl_add_u32 v38, v38, 4, v12
	v_lshl_add_u32 v39, v39, 4, v27
	v_lshl_add_u32 v22, v22, 4, v31
	v_or_b32_e32 v34, v34, v33
	v_or_b32_e32 v35, v35, v33
	v_or_b32_e32 v36, v36, v33
	v_or_b32_e32 v37, v37, v33
	v_or_b32_e32 v38, v38, v33
	v_or_b32_e32 v39, v39, v33
	v_or_b32_e32 v22, v22, v33
	ds_read_b32 v34, v34
	ds_read_b32 v35, v35
	ds_read_b32 v36, v36
	ds_read_b32 v37, v37
	ds_read_b32 v38, v38
	ds_read_b32 v39, v39
	ds_read_b32 v22, v22
	v_add_u32_e32 v32, s6, v32
	v_ashrrev_i32_e32 v33, 31, v32
	v_lshlrev_b64 v[32:33], 12, v[32:33]
	v_lshl_add_u64 v[32:33], s[14:15], 0, v[32:33]
	v_lshl_add_u64 v[32:33], v[32:33], 0, s[0:1]
	s_waitcnt lgkmcnt(5)
	v_cvt_pk_bf16_f32 v34, v34, v35
	s_waitcnt lgkmcnt(3)
	v_cvt_pk_bf16_f32 v35, v36, v37
	s_waitcnt lgkmcnt(1)
	v_cvt_pk_bf16_f32 v36, v38, v39
	s_waitcnt lgkmcnt(0)
	v_cvt_pk_bf16_f32 v37, v40, v22
	v_lshl_add_u64 v[32:33], v[32:33], 0, v[10:11]
	v_ashrrev_i32_e32 v20, 6, v20
	global_store_dwordx4 v[32:33], v[34:37], off
	v_lshlrev_b32_e32 v22, 2, v25
	v_bitop3_b32 v32, v0, v20, 24 bitop3:0x6c
	v_bitop3_b32 v33, v3, v20, 25 bitop3:0x6c
	v_bitop3_b32 v34, v5, v20, 26 bitop3:0x6c
	v_bitop3_b32 v35, v7, v20, 27 bitop3:0x6c
	v_bitop3_b32 v36, v9, v20, 28 bitop3:0x6c
	v_bitop3_b32 v37, v26, v20, 29 bitop3:0x6c
	v_and_b32_e32 v22, 12, v22
	v_lshl_add_u32 v32, v32, 4, v2
	v_lshl_add_u32 v33, v33, 4, v4
	v_lshl_add_u32 v34, v34, 4, v6
	v_lshl_add_u32 v35, v35, 4, v8
	v_lshl_add_u32 v36, v36, 4, v12
	v_lshl_add_u32 v37, v37, 4, v27
	v_or_b32_e32 v32, v32, v22
	v_or_b32_e32 v33, v33, v22
	v_or_b32_e32 v34, v34, v22
	v_or_b32_e32 v35, v35, v22
	v_or_b32_e32 v36, v36, v22
	v_or_b32_e32 v37, v37, v22
	ds_read_b32 v32, v32
	ds_read_b32 v33, v33
	ds_read_b32 v34, v34
	ds_read_b32 v35, v35
	ds_read_b32 v36, v36
	ds_read_b32 v37, v37
	v_bitop3_b32 v38, v28, v20, 30 bitop3:0x6c
	v_bitop3_b32 v20, v30, v20, 31 bitop3:0x6c
	v_lshl_add_u32 v38, v38, 4, v29
	v_lshl_add_u32 v20, v20, 4, v31
	v_or_b32_e32 v38, v38, v22
	v_or_b32_e32 v20, v20, v22
	ds_read_b32 v38, v38
	ds_read_b32 v20, v20
	s_waitcnt lgkmcnt(6)
	v_cvt_pk_bf16_f32 v32, v32, v33
	s_waitcnt lgkmcnt(4)
	v_cvt_pk_bf16_f32 v33, v34, v35
	s_waitcnt lgkmcnt(2)
	v_cvt_pk_bf16_f32 v34, v36, v37
	v_add_u32_e32 v36, s6, v25
	v_ashrrev_i32_e32 v37, 31, v36
	v_lshlrev_b64 v[36:37], 12, v[36:37]
	v_lshl_add_u64 v[36:37], s[14:15], 0, v[36:37]
	v_lshl_add_u64 v[36:37], v[36:37], 0, s[0:1]
	s_waitcnt lgkmcnt(0)
	v_cvt_pk_bf16_f32 v35, v38, v20
	v_lshl_add_u64 v[36:37], v[36:37], 0, v[10:11]
	v_ashrrev_i32_e32 v18, 6, v18
	global_store_dwordx4 v[36:37], v[32:35], off
	v_lshlrev_b32_e32 v20, 2, v24
	v_bitop3_b32 v22, v0, v18, 24 bitop3:0x6c
	v_bitop3_b32 v25, v3, v18, 25 bitop3:0x6c
	v_bitop3_b32 v32, v5, v18, 26 bitop3:0x6c
	v_and_b32_e32 v20, 12, v20
	v_lshl_add_u32 v22, v22, 4, v2
	v_lshl_add_u32 v25, v25, 4, v4
	v_lshl_add_u32 v32, v32, 4, v6
	v_or_b32_e32 v22, v22, v20
	v_or_b32_e32 v25, v25, v20
	v_or_b32_e32 v32, v32, v20
	ds_read_b32 v22, v22
	ds_read_b32 v25, v25
	ds_read_b32 v33, v32
	v_bitop3_b32 v32, v7, v18, 27 bitop3:0x6c
	v_lshl_add_u32 v32, v32, 4, v8
	v_or_b32_e32 v32, v32, v20
	ds_read_b32 v34, v32
	v_bitop3_b32 v32, v9, v18, 28 bitop3:0x6c
	v_lshl_add_u32 v32, v32, 4, v12
	v_or_b32_e32 v32, v32, v20
	ds_read_b32 v35, v32
	v_bitop3_b32 v32, v26, v18, 29 bitop3:0x6c
	v_lshl_add_u32 v32, v32, 4, v27
	v_or_b32_e32 v32, v32, v20
	ds_read_b32 v36, v32
	v_bitop3_b32 v32, v28, v18, 30 bitop3:0x6c
	v_bitop3_b32 v18, v30, v18, 31 bitop3:0x6c
	v_lshl_add_u32 v32, v32, 4, v29
	v_lshl_add_u32 v18, v18, 4, v31
	v_or_b32_e32 v32, v32, v20
	v_or_b32_e32 v18, v18, v20
	ds_read_b32 v37, v32
	ds_read_b32 v18, v18
	v_add_u32_e32 v24, s6, v24
	s_waitcnt lgkmcnt(6)
	v_cvt_pk_bf16_f32 v32, v22, v25
	v_ashrrev_i32_e32 v25, 31, v24
	v_lshlrev_b64 v[24:25], 12, v[24:25]
	v_lshl_add_u64 v[24:25], s[14:15], 0, v[24:25]
	v_lshl_add_u64 v[24:25], v[24:25], 0, s[0:1]
	s_waitcnt lgkmcnt(4)
	v_cvt_pk_bf16_f32 v33, v33, v34
	s_waitcnt lgkmcnt(2)
	v_cvt_pk_bf16_f32 v34, v35, v36
	s_waitcnt lgkmcnt(0)
	v_cvt_pk_bf16_f32 v35, v37, v18
	v_lshl_add_u64 v[24:25], v[24:25], 0, v[10:11]
	v_ashrrev_i32_e32 v17, 6, v17
	global_store_dwordx4 v[24:25], v[32:35], off
	v_lshlrev_b32_e32 v18, 2, v23
	v_bitop3_b32 v20, v0, v17, 24 bitop3:0x6c
	v_bitop3_b32 v22, v3, v17, 25 bitop3:0x6c
	v_bitop3_b32 v24, v5, v17, 26 bitop3:0x6c
	v_bitop3_b32 v25, v7, v17, 27 bitop3:0x6c
	v_bitop3_b32 v32, v9, v17, 28 bitop3:0x6c
	v_and_b32_e32 v18, 12, v18
	v_lshl_add_u32 v20, v20, 4, v2
	v_lshl_add_u32 v22, v22, 4, v4
	v_lshl_add_u32 v24, v24, 4, v6
	v_lshl_add_u32 v25, v25, 4, v8
	v_lshl_add_u32 v32, v32, 4, v12
	v_or_b32_e32 v20, v20, v18
	v_or_b32_e32 v22, v22, v18
	v_or_b32_e32 v24, v24, v18
	v_or_b32_e32 v25, v25, v18
	v_or_b32_e32 v32, v32, v18
	ds_read_b32 v20, v20
	ds_read_b32 v22, v22
	ds_read_b32 v24, v24
	ds_read_b32 v25, v25
	ds_read_b32 v34, v32
	v_bitop3_b32 v32, v26, v17, 29 bitop3:0x6c
	v_lshl_add_u32 v32, v32, 4, v27
	v_or_b32_e32 v32, v32, v18
	ds_read_b32 v35, v32
	v_bitop3_b32 v32, v28, v17, 30 bitop3:0x6c
	v_bitop3_b32 v17, v30, v17, 31 bitop3:0x6c
	v_lshl_add_u32 v32, v32, 4, v29
	v_lshl_add_u32 v17, v17, 4, v31
	v_or_b32_e32 v32, v32, v18
	v_or_b32_e32 v17, v17, v18
	ds_read_b32 v36, v32
	ds_read_b32 v17, v17
	s_waitcnt lgkmcnt(6)
; __device__ void phaseA_tile(const Params& p, int l, int mt, int nt, char* smem) {
;     ...
;                     const int b = m0 >> 11, t0 = m0 & 2047;
; #pragma unroll
;                     for (int it = 0; it < 8; ++it) {
;                         const int idx = it * 256 + tid;
;                         const int tg = idx & 15, c = idx >> 4;
;                         float f[8];
; #pragma unroll
;                         for (int e = 0; e < 8; ++e) {
;                             const int rl = tg * 8 + e;
;                             f[e] = *(const float*)(smem + rl * 512 + (((c >> 2) ^ (rl & 31)) << 4) + (c & 3) * 4);
;                         }
;                         *(uint4*)(p.vT + ((size_t)(b * 1024 + c0 + c)) * 2048 + t0 + tg * 8) =
;                             make_uint4(pk2(f[0], f[1]), pk2(f[2], f[3]), pk2(f[4], f[5]), pk2(f[6], f[7]));
;                     }
	v_cvt_pk_bf16_f32 v32, v20, v22
	v_add_u32_e32 v22, s6, v23
	v_ashrrev_i32_e32 v23, 31, v22
	v_lshlrev_b64 v[22:23], 12, v[22:23]
	v_lshl_add_u64 v[22:23], s[14:15], 0, v[22:23]
	v_lshl_add_u64 v[22:23], v[22:23], 0, s[0:1]
	s_waitcnt lgkmcnt(4)
	v_cvt_pk_bf16_f32 v33, v24, v25
	s_waitcnt lgkmcnt(2)
	v_cvt_pk_bf16_f32 v34, v34, v35
	s_waitcnt lgkmcnt(0)
	v_cvt_pk_bf16_f32 v35, v36, v17
	v_lshl_add_u64 v[22:23], v[22:23], 0, v[10:11]
	v_ashrrev_i32_e32 v15, 6, v15
	global_store_dwordx4 v[22:23], v[32:35], off
	v_lshlrev_b32_e32 v17, 2, v21
	v_bitop3_b32 v18, v0, v15, 24 bitop3:0x6c
	v_bitop3_b32 v20, v3, v15, 25 bitop3:0x6c
	v_bitop3_b32 v22, v5, v15, 26 bitop3:0x6c
	v_and_b32_e32 v17, 12, v17
	v_lshl_add_u32 v18, v18, 4, v2
	v_lshl_add_u32 v20, v20, 4, v4
	v_lshl_add_u32 v22, v22, 4, v6
	v_or_b32_e32 v18, v18, v17
	v_or_b32_e32 v20, v20, v17
	v_or_b32_e32 v22, v22, v17
	ds_read_b32 v18, v18
	ds_read_b32 v20, v20
	ds_read_b32 v23, v22
	v_bitop3_b32 v22, v7, v15, 27 bitop3:0x6c
	v_lshl_add_u32 v22, v22, 4, v8
	v_or_b32_e32 v22, v22, v17
	ds_read_b32 v24, v22
	v_bitop3_b32 v22, v9, v15, 28 bitop3:0x6c
	v_lshl_add_u32 v22, v22, 4, v12
	v_or_b32_e32 v22, v22, v17
	ds_read_b32 v25, v22
	v_bitop3_b32 v22, v26, v15, 29 bitop3:0x6c
	v_lshl_add_u32 v22, v22, 4, v27
	v_or_b32_e32 v22, v22, v17
	ds_read_b32 v32, v22
	v_bitop3_b32 v22, v28, v15, 30 bitop3:0x6c
	v_bitop3_b32 v15, v30, v15, 31 bitop3:0x6c
	v_lshl_add_u32 v22, v22, 4, v29
	v_lshl_add_u32 v15, v15, 4, v31
	v_or_b32_e32 v22, v22, v17
	v_or_b32_e32 v15, v15, v17
	ds_read_b32 v33, v22
	ds_read_b32 v15, v15
	s_waitcnt lgkmcnt(6)
	v_cvt_pk_bf16_f32 v22, v18, v20
	v_add_u32_e32 v20, s6, v21
	v_ashrrev_i32_e32 v21, 31, v20
	v_lshlrev_b64 v[20:21], 12, v[20:21]
	v_lshl_add_u64 v[20:21], s[14:15], 0, v[20:21]
	v_lshl_add_u64 v[20:21], v[20:21], 0, s[0:1]
	s_waitcnt lgkmcnt(4)
	v_cvt_pk_bf16_f32 v23, v23, v24
	s_waitcnt lgkmcnt(2)
	v_cvt_pk_bf16_f32 v24, v25, v32
	s_waitcnt lgkmcnt(0)
	v_cvt_pk_bf16_f32 v25, v33, v15
	v_lshl_add_u64 v[20:21], v[20:21], 0, v[10:11]
	v_ashrrev_i32_e32 v14, 6, v14
	global_store_dwordx4 v[20:21], v[22:25], off
	v_lshlrev_b32_e32 v15, 2, v19
	v_bitop3_b32 v17, v0, v14, 24 bitop3:0x6c
	v_bitop3_b32 v18, v3, v14, 25 bitop3:0x6c
	v_bitop3_b32 v20, v5, v14, 26 bitop3:0x6c
	v_and_b32_e32 v15, 12, v15
	v_lshl_add_u32 v17, v17, 4, v2
	v_lshl_add_u32 v18, v18, 4, v4
	v_lshl_add_u32 v20, v20, 4, v6
	v_or_b32_e32 v17, v17, v15
	v_or_b32_e32 v18, v18, v15
	v_or_b32_e32 v20, v20, v15
	ds_read_b32 v17, v17
	ds_read_b32 v18, v18
	ds_read_b32 v21, v20
	v_bitop3_b32 v20, v7, v14, 27 bitop3:0x6c
	v_lshl_add_u32 v20, v20, 4, v8
	v_or_b32_e32 v20, v20, v15
	ds_read_b32 v22, v20
	v_bitop3_b32 v20, v9, v14, 28 bitop3:0x6c
	v_lshl_add_u32 v20, v20, 4, v12
	v_or_b32_e32 v20, v20, v15
	ds_read_b32 v23, v20
	v_bitop3_b32 v20, v26, v14, 29 bitop3:0x6c
	v_lshl_add_u32 v20, v20, 4, v27
	v_or_b32_e32 v20, v20, v15
	ds_read_b32 v24, v20
	v_bitop3_b32 v20, v28, v14, 30 bitop3:0x6c
	v_bitop3_b32 v14, v30, v14, 31 bitop3:0x6c
	v_lshl_add_u32 v20, v20, 4, v29
	v_lshl_add_u32 v14, v14, 4, v31
	v_or_b32_e32 v20, v20, v15
	v_or_b32_e32 v14, v14, v15
	ds_read_b32 v25, v20
	ds_read_b32 v14, v14
	s_waitcnt lgkmcnt(4)
	v_cvt_pk_bf16_f32 v21, v21, v22
	s_waitcnt lgkmcnt(2)
	v_cvt_pk_bf16_f32 v22, v23, v24
	v_cvt_pk_bf16_f32 v20, v17, v18
	v_readlane_b32 s9, v214, 51
	s_waitcnt lgkmcnt(0)
	v_cvt_pk_bf16_f32 v23, v25, v14
	v_add_u32_e32 v14, s6, v19
	v_ashrrev_i32_e32 v15, 31, v14
	v_lshlrev_b64 v[14:15], 12, v[14:15]
	v_lshl_add_u64 v[14:15], s[14:15], 0, v[14:15]
	v_lshl_add_u64 v[14:15], v[14:15], 0, s[0:1]
	v_lshl_add_u64 v[10:11], v[14:15], 0, v[10:11]
	global_store_dwordx4 v[10:11], v[20:23], off
	v_ashrrev_i32_e32 v10, 6, v13
	v_bitop3_b32 v3, v3, v10, 25 bitop3:0x6c
	v_lshl_add_u32 v3, v3, 4, v4
	v_bitop3_b32 v4, v5, v10, 26 bitop3:0x6c
	v_bitop3_b32 v5, v7, v10, 27 bitop3:0x6c
	v_lshlrev_b32_e32 v11, 2, v16
	v_bitop3_b32 v13, v0, v10, 24 bitop3:0x6c
	v_lshl_add_u32 v4, v4, 4, v6
	v_lshl_add_u32 v5, v5, 4, v8
	v_bitop3_b32 v6, v9, v10, 28 bitop3:0x6c
	v_bitop3_b32 v7, v26, v10, 29 bitop3:0x6c
	v_bitop3_b32 v8, v28, v10, 30 bitop3:0x6c
	v_bitop3_b32 v9, v30, v10, 31 bitop3:0x6c
	v_and_b32_e32 v11, 12, v11
	v_lshl_add_u32 v2, v13, 4, v2
	v_lshl_add_u32 v6, v6, 4, v12
	v_lshl_add_u32 v7, v7, 4, v27
	v_lshl_add_u32 v8, v8, 4, v29
	v_lshl_add_u32 v9, v9, 4, v31
	v_or_b32_e32 v2, v2, v11
	v_or_b32_e32 v3, v3, v11
	v_or_b32_e32 v4, v4, v11
	v_or_b32_e32 v5, v5, v11
	v_or_b32_e32 v6, v6, v11
	v_or_b32_e32 v7, v7, v11
	v_or_b32_e32 v8, v8, v11
	v_or_b32_e32 v9, v9, v11
	ds_read_b32 v2, v2
	ds_read_b32 v3, v3
	ds_read_b32 v4, v4
	ds_read_b32 v5, v5
	ds_read_b32 v6, v6
	ds_read_b32 v7, v7
	ds_read_b32 v8, v8
	ds_read_b32 v9, v9
	v_add_u32_e32 v12, s6, v16
	s_mov_b64 s[6:7], 12
	s_mov_b64 s[0:1], s[2:3]
	v_readlane_b32 s10, v214, 52
	v_readlane_b32 s11, v214, 53
	v_readlane_b32 s12, v214, 54
	v_readlane_b32 s13, v214, 55
	v_readlane_b32 s16, v214, 58
	v_readlane_b32 s17, v214, 59
	v_readlane_b32 s18, v214, 60
	v_readlane_b32 s19, v214, 61
	v_readlane_b32 s20, v214, 62
	v_readlane_b32 s21, v214, 63
	v_readlane_b32 s22, v213, 0
	v_readlane_b32 s23, v213, 1

; __device__ __forceinline__ float bf_lo(unsigned u) { return __uint_as_float(u << 16); }
; __device__ __forceinline__ float bf_hi(unsigned u) { return __uint_as_float(u & 0xffff0000u); }
; __device__ __forceinline__ float bf2f(u16 v) { return __uint_as_float(((unsigned)v) << 16); }
; __device__ __forceinline__ float siluf(float x) { return x * frcp(1.f + __expf(-x)); }
; __device__ void ssd_item(const Params& p, int l, bool samp, int b, int h, char* smem) {
;     ...
;         {
;             float ssq = 0.f;
; #pragma unroll
;             for (int pt = 0; pt < 4; ++pt) {
;                 const int p0 = 16 * pt + 4 * g4;
;                 float y[4];
; #pragma unroll
;                 for (int e = 0; e < 4; ++e) {
;                     const int pp = p0 + e;
;                     const u16 xv = *(const u16*)(xT + pp * 128 + (((ll >> 3) ^ (pp & 7)) << 4) + (ll & 7) * 2);
;                     y[e] = fmaf(Dh, bf2f(xv), acc[pt][e]);
;                 }
;                 const uint2 zz = zz4[pt];
;                 y[0] *= siluf(bf_lo(zz.x)); y[1] *= siluf(bf_hi(zz.x)); y[2] *= siluf(bf_lo(zz.y)); y[3] *= siluf(bf_hi(zz.y));
;                 ssq += y[0] * y[0] + y[1] * y[1] + y[2] * y[2] + y[3] * y[3];
;                 if (valid) *(uint2*)(p.ygb + tok * 2048 + h * 64 + p0) = make_uint2(pk2(y[0], y[1]), pk2(y[2], y[3]));
;             }
.LBB0_556:
	ds_read_u16 v54, v177 offset:49152
	ds_read_u16 v55, v178 offset:49152
	s_waitcnt vmcnt(8)
	v_lshlrev_b32_e32 v52, 16, v122
	v_and_b32_e32 v53, 0xffff0000, v122
	s_waitcnt lgkmcnt(0)
	v_lshlrev_b32_e32 v54, 16, v54
	v_lshlrev_b32_e32 v55, 16, v55
	v_pk_fma_f32 v[48:49], v[78:79], v[54:55], v[48:49]
	v_mul_f32_e32 v54, 0xbfb8aa3b, v52
	v_mul_f32_e32 v55, 0xbfb8aa3b, v53
	v_exp_f32_e32 v54, v54
	v_exp_f32_e32 v55, v55
	v_add_f32_e32 v54, 1.0, v54
	v_add_f32_e32 v55, 1.0, v55
	v_rcp_f32_e32 v54, v54
	v_rcp_f32_e32 v55, v55
	s_nop 0
	v_pk_mul_f32 v[52:53], v[54:55], v[52:53]
	ds_read_u16 v54, v179 offset:49152
	ds_read_u16 v55, v180 offset:49152
	v_pk_mul_f32 v[48:49], v[52:53], v[48:49]
	v_lshlrev_b32_e32 v52, 16, v123
	v_and_b32_e32 v53, 0xffff0000, v123
	s_waitcnt lgkmcnt(1)
	v_lshlrev_b32_e32 v54, 16, v54
	s_waitcnt lgkmcnt(0)
	v_lshlrev_b32_e32 v55, 16, v55
	v_pk_fma_f32 v[50:51], v[78:79], v[54:55], v[50:51]
	v_mul_f32_e32 v54, 0xbfb8aa3b, v52
	v_mul_f32_e32 v55, 0xbfb8aa3b, v53
	v_exp_f32_e32 v54, v54
	v_exp_f32_e32 v55, v55
	v_add_f32_e32 v54, 1.0, v54
	v_add_f32_e32 v55, 1.0, v55
	v_rcp_f32_e32 v54, v54
	v_rcp_f32_e32 v55, v55
	s_nop 0
	v_pk_mul_f32 v[52:53], v[54:55], v[52:53]
	s_nop 0
	v_pk_mul_f32 v[50:51], v[52:53], v[50:51]
	v_lshl_add_u64 v[52:53], v[124:125], 1, v[84:85]
	s_and_saveexec_b64 s[72:73], s[60:61]
	s_cbranch_execz .LBB0_558
	v_cvt_pk_bf16_f32 v54, v48, v49
	v_cvt_pk_bf16_f32 v55, v50, v51
	global_store_dwordx2 v[52:53], v[54:55], off

; #define MFMA(a, b, c) __builtin_amdgcn_mfma_f32_16x16x32_bf16((a), (b), (c), 0, 0, 0)
; template <int AMODE>
; __device__ __forceinline__ void gemm_kloop(f32x4 (&acc)[4][4], const u16* __restrict__ A, int lda,
;                                            const u16* __restrict__ Bt, int ldb, int K, char* smem,
;                                            const float* __restrict__ ssq_rows) {
;     ...
;     for (int kt = 0; kt < nk; ++kt) {
;         const int buf = kt & 1;
;         if (kt + 1 < nk) GLOAD(kt + 1, buf ^ 1);
;         const char* ab = As + buf * 16384 + (wr * 64 + r) * 128;
;         const char* bb = Bs + buf * 16384 + (wc * 64 + r) * 128;
;         bf16x8 af[2][4], bfr[2][4];
; #pragma unroll
;         for (int ks = 0; ks < 2; ++ks) {
;             const int co = ((ks * 4 + g4) ^ (r & 7)) << 4;
; #pragma unroll
;             for (int i = 0; i < 4; ++i) af[ks][i] = ld_frag(ab + i * 2048 + co);
; #pragma unroll
;             for (int j = 0; j < 4; ++j) bfr[ks][j] = ld_frag(bb + j * 2048 + co);
;         }
;         __builtin_amdgcn_sched_barrier(0);
;         __builtin_amdgcn_s_setprio(1);
; #pragma unroll
;         for (int ks = 0; ks < 2; ++ks)
; #pragma unroll
;             for (int i = 0; i < 4; ++i)
; #pragma unroll
;                 for (int j = 0; j < 4; ++j) acc[i][j] = MFMA(bfr[ks][j], af[ks][i], acc[i][j]);
;         __builtin_amdgcn_s_setprio(0);
;         __builtin_amdgcn_sched_barrier(0);
;         if (kt + 1 < nk) LSTORE(buf ^ 1);
;         asm volatile("s_waitcnt vmcnt(0)" ::: "memory");
;         __syncthreads();
;     }
.LBB0_707:
	s_and_b32 s18, s17, 0x4000
	s_xor_b32 s19, s18, 0x4000
	v_add_u32_e32 v0, s19, v70
	v_add_u32_e32 v75, 0x8000, v0
	v_lshl_add_u64 v[76:77], v[66:67], 0, s[12:13]
	v_readfirstlane_b32 s19, v75
	v_lshl_add_u64 v[78:79], v[76:77], 0, s[62:63]
	v_lshl_add_u64 v[80:81], v[68:69], 0, s[12:13]
	s_mov_b32 m0, s19
	v_readfirstlane_b32 s19, v0
	v_add_u32_e32 v75, 0x9000, v0
	v_lshl_add_u64 v[82:83], v[80:81], 0, s[62:63]
	global_load_lds_dwordx4 v[78:79], off
	s_mov_b32 m0, s19
	v_readfirstlane_b32 s19, v75
	v_add_u32_e32 v75, 0x1000, v0
	global_load_lds_dwordx4 v[82:83], off
	v_lshl_add_u64 v[78:79], v[76:77], 0, s[64:65]
	s_mov_b32 m0, s19
	v_readfirstlane_b32 s19, v75
	v_add_u32_e32 v75, 0xa000, v0
	global_load_lds_dwordx4 v[78:79], off
	v_lshl_add_u64 v[78:79], v[80:81], 0, s[64:65]
	s_mov_b32 m0, s19
	v_readfirstlane_b32 s19, v75
	v_add_u32_e32 v75, 0x2000, v0
	global_load_lds_dwordx4 v[78:79], off
	v_lshl_add_u64 v[78:79], v[76:77], 0, s[20:21]
	s_mov_b32 m0, s19
	v_readfirstlane_b32 s19, v75
	v_add_u32_e32 v75, 0xb000, v0
	global_load_lds_dwordx4 v[78:79], off
	v_lshl_add_u64 v[78:79], v[80:81], 0, s[20:21]
	s_mov_b32 m0, s19
	v_readfirstlane_b32 s19, v75
	v_add_u32_e32 v0, 0x3000, v0
	global_load_lds_dwordx4 v[78:79], off
	v_lshl_add_u64 v[76:77], v[76:77], 0, s[22:23]
	s_mov_b32 m0, s19
	v_readfirstlane_b32 s19, v0
	global_load_lds_dwordx4 v[76:77], off
	v_lshl_add_u64 v[76:77], v[80:81], 0, s[22:23]
	s_mov_b32 m0, s19
	v_add_u32_e32 v0, s18, v72
	global_load_lds_dwordx4 v[76:77], off
	v_or_b32_e32 v75, s18, v71
	v_add_u32_e32 v90, v0, v74
	v_add_u32_e32 v102, v75, v74
	v_add_u32_e32 v0, v0, v73
	ds_read_b128 v[76:79], v90
	ds_read_b128 v[80:83], v90 offset:2048
	ds_read_b128 v[84:87], v90 offset:4096
	ds_read_b128 v[90:93], v90 offset:6144
	ds_read_b128 v[94:97], v102 offset:32768
	ds_read_b128 v[98:101], v102 offset:34816
	ds_read_b128 v[110:113], v102 offset:36864
	ds_read_b128 v[114:117], v102 offset:38912
	ds_read_b128 v[118:121], v0
	ds_read_b128 v[122:125], v0 offset:2048
	ds_read_b128 v[126:129], v0 offset:4096
	ds_read_b128 v[130:133], v0 offset:6144
	v_add_u32_e32 v0, v75, v73
	ds_read_b128 v[134:137], v0 offset:32768
	ds_read_b128 v[142:145], v0 offset:34816
	ds_read_b128 v[146:149], v0 offset:36864
	ds_read_b128 v[150:153], v0 offset:38912
	s_setprio 1
	s_waitcnt lgkmcnt(0)
	v_mfma_f32_16x16x32_bf16 v[62:65], v[94:97], v[76:79], v[62:65]
	v_mfma_f32_16x16x32_bf16 v[58:61], v[98:101], v[76:79], v[58:61]
	v_mfma_f32_16x16x32_bf16 v[54:57], v[110:113], v[76:79], v[54:57]
	v_mfma_f32_16x16x32_bf16 v[50:53], v[114:117], v[76:79], v[50:53]
	v_mfma_f32_16x16x32_bf16 v[46:49], v[94:97], v[80:83], v[46:49]
	v_mfma_f32_16x16x32_bf16 v[42:45], v[98:101], v[80:83], v[42:45]
	v_mfma_f32_16x16x32_bf16 v[38:41], v[110:113], v[80:83], v[38:41]
	v_mfma_f32_16x16x32_bf16 v[34:37], v[114:117], v[80:83], v[34:37]
	v_mfma_f32_16x16x32_bf16 v[30:33], v[94:97], v[84:87], v[30:33]
	v_mfma_f32_16x16x32_bf16 v[26:29], v[98:101], v[84:87], v[26:29]
	v_mfma_f32_16x16x32_bf16 v[22:25], v[110:113], v[84:87], v[22:25]
	v_mfma_f32_16x16x32_bf16 v[18:21], v[114:117], v[84:87], v[18:21]
	v_mfma_f32_16x16x32_bf16 v[14:17], v[94:97], v[90:93], v[14:17]
	v_mfma_f32_16x16x32_bf16 v[10:13], v[98:101], v[90:93], v[10:13]
	v_mfma_f32_16x16x32_bf16 v[6:9], v[110:113], v[90:93], v[6:9]
	v_mfma_f32_16x16x32_bf16 v[2:5], v[114:117], v[90:93], v[2:5]
	v_mfma_f32_16x16x32_bf16 v[62:65], v[134:137], v[118:121], v[62:65]
	v_mfma_f32_16x16x32_bf16 v[58:61], v[142:145], v[118:121], v[58:61]
	v_mfma_f32_16x16x32_bf16 v[54:57], v[146:149], v[118:121], v[54:57]
	v_mfma_f32_16x16x32_bf16 v[50:53], v[150:153], v[118:121], v[50:53]
	v_mfma_f32_16x16x32_bf16 v[46:49], v[134:137], v[122:125], v[46:49]
	v_mfma_f32_16x16x32_bf16 v[42:45], v[142:145], v[122:125], v[42:45]
	v_mfma_f32_16x16x32_bf16 v[38:41], v[146:149], v[122:125], v[38:41]
	v_mfma_f32_16x16x32_bf16 v[34:37], v[150:153], v[122:125], v[34:37]
	v_mfma_f32_16x16x32_bf16 v[30:33], v[134:137], v[126:129], v[30:33]
	v_mfma_f32_16x16x32_bf16 v[26:29], v[142:145], v[126:129], v[26:29]
	v_mfma_f32_16x16x32_bf16 v[22:25], v[146:149], v[126:129], v[22:25]
	v_mfma_f32_16x16x32_bf16 v[18:21], v[150:153], v[126:129], v[18:21]
	v_mfma_f32_16x16x32_bf16 v[14:17], v[134:137], v[130:133], v[14:17]
	v_mfma_f32_16x16x32_bf16 v[10:13], v[142:145], v[130:133], v[10:13]
	v_mfma_f32_16x16x32_bf16 v[6:9], v[146:149], v[130:133], v[6:9]
	v_mfma_f32_16x16x32_bf16 v[2:5], v[150:153], v[130:133], v[2:5]
	s_setprio 0
	s_waitcnt vmcnt(0)
	s_add_u32 s12, s12, 0x80
	s_addc_u32 s13, s13, 0
	s_addk_i32 s17, 0x4000
	s_cmpk_eq_i32 s12, 0xf80
	s_waitcnt vmcnt(0)
	s_barrier
	s_cbranch_scc0 .LBB0_707
; __device__ __forceinline__ float bf_lo(unsigned u) { return __uint_as_float(u << 16); }
; __device__ __forceinline__ float bf_hi(unsigned u) { return __uint_as_float(u & 0xffff0000u); }
; __device__ __forceinline__ float frcp(float x) { return __builtin_amdgcn_rcpf(x); }
; #define MFMA(a, b, c) __builtin_amdgcn_mfma_f32_16x16x32_bf16((a), (b), (c), 0, 0, 0)
; template <int AMODE>
; __device__ __forceinline__ void gemm_kloop(f32x4 (&acc)[4][4], const u16* __restrict__ A, int lda,
;                                            const u16* __restrict__ Bt, int ldb, int K, char* smem,
;                                            const float* __restrict__ ssq_rows) {
;     ...
; #pragma unroll
;         for (int ks = 0; ks < 2; ++ks)
; #pragma unroll
;             for (int i = 0; i < 4; ++i)
; #pragma unroll
;                 for (int j = 0; j < 4; ++j) acc[i][j] = MFMA(bfr[ks][j], af[ks][i], acc[i][j]);
;         __builtin_amdgcn_s_setprio(0);
;         __builtin_amdgcn_sched_barrier(0);
; __device__ void phaseC1(const Params& p, int l, char* smem) {
;     ...
; #pragma unroll
;         for (int i = 0; i < 4; ++i) {
;             const size_t row = (size_t)(m0 + wr * 64 + i * 16 + r);
; #pragma unroll
;             for (int j = 0; j < 4; ++j) {
;                 const int col = n0 + wc * 64 + j * 16 + g4 * 4;
;                 const uint2 gm = *(const uint2*)(p.gmb + row * 1024 + col);
;                 const uint2 ga = *(const uint2*)(p.gab + row * 1024 + col);
;                 acc[i][j][0] *= bf_lo(gm.x) * frcp(bf_lo(ga.x)); acc[i][j][1] *= bf_hi(gm.x) * frcp(bf_hi(ga.x));
;                 acc[i][j][2] *= bf_lo(gm.y) * frcp(bf_lo(ga.y)); acc[i][j][3] *= bf_hi(gm.y) * frcp(bf_hi(ga.y));
;             }
;         }
	v_add_u32_e32 v0, v72, v74
	ds_read_b128 v[66:69], v0 offset:16384
	ds_read_b128 v[76:79], v0 offset:18432
	ds_read_b128 v[80:83], v0 offset:20480
	ds_read_b128 v[84:87], v0 offset:22528
	v_add_u32_e32 v0, v71, v74
	ds_read_b128 v[90:93], v0 offset:49152
	ds_read_b128 v[94:97], v0 offset:51200
	ds_read_b128 v[98:101], v0 offset:53248
	ds_read_b128 v[110:113], v0 offset:55296
	v_add_u32_e32 v0, v72, v73
	ds_read_b128 v[114:117], v0 offset:16384
	ds_read_b128 v[118:121], v0 offset:18432
	ds_read_b128 v[122:125], v0 offset:20480
	ds_read_b128 v[126:129], v0 offset:22528
	v_add_u32_e32 v0, v71, v73
	ds_read_b128 v[70:73], v0 offset:49152
	ds_read_b128 v[130:133], v0 offset:51200
	ds_read_b128 v[134:137], v0 offset:53248
	ds_read_b128 v[142:145], v0 offset:55296
	s_setprio 1
	s_waitcnt lgkmcnt(11)
	v_mfma_f32_16x16x32_bf16 v[62:65], v[90:93], v[66:69], v[62:65]
	s_waitcnt lgkmcnt(10)
	v_mfma_f32_16x16x32_bf16 v[58:61], v[94:97], v[66:69], v[58:61]
	s_waitcnt lgkmcnt(9)
	v_mfma_f32_16x16x32_bf16 v[54:57], v[98:101], v[66:69], v[54:57]
	s_waitcnt lgkmcnt(8)
	v_mfma_f32_16x16x32_bf16 v[50:53], v[110:113], v[66:69], v[50:53]
	v_mfma_f32_16x16x32_bf16 v[46:49], v[90:93], v[76:79], v[46:49]
	v_mfma_f32_16x16x32_bf16 v[42:45], v[94:97], v[76:79], v[42:45]
	v_mfma_f32_16x16x32_bf16 v[38:41], v[98:101], v[76:79], v[38:41]
	v_mfma_f32_16x16x32_bf16 v[34:37], v[110:113], v[76:79], v[34:37]
	v_mfma_f32_16x16x32_bf16 v[66:69], v[90:93], v[80:83], v[30:33]
	v_mfma_f32_16x16x32_bf16 v[26:29], v[94:97], v[80:83], v[26:29]
	v_mfma_f32_16x16x32_bf16 v[74:77], v[98:101], v[80:83], v[22:25]
	v_mfma_f32_16x16x32_bf16 v[78:81], v[110:113], v[80:83], v[18:21]
	v_mfma_f32_16x16x32_bf16 v[90:93], v[90:93], v[84:87], v[14:17]
	v_mfma_f32_16x16x32_bf16 v[10:13], v[94:97], v[84:87], v[10:13]
	v_mfma_f32_16x16x32_bf16 v[6:9], v[98:101], v[84:87], v[6:9]
	v_mfma_f32_16x16x32_bf16 v[2:5], v[110:113], v[84:87], v[2:5]
	s_waitcnt lgkmcnt(3)
	v_mfma_f32_16x16x32_bf16 v[82:85], v[70:73], v[114:117], v[62:65]
	s_waitcnt lgkmcnt(2)
	v_mfma_f32_16x16x32_bf16 v[94:97], v[130:133], v[114:117], v[58:61]
	s_waitcnt lgkmcnt(1)
	v_mfma_f32_16x16x32_bf16 v[98:101], v[134:137], v[114:117], v[54:57]
	s_waitcnt lgkmcnt(0)
	v_mfma_f32_16x16x32_bf16 v[14:17], v[142:145], v[114:117], v[50:53]
	v_mfma_f32_16x16x32_bf16 v[18:21], v[70:73], v[118:121], v[46:49]
	v_mfma_f32_16x16x32_bf16 v[22:25], v[130:133], v[118:121], v[42:45]
	v_mfma_f32_16x16x32_bf16 v[30:33], v[134:137], v[118:121], v[38:41]
	v_mfma_f32_16x16x32_bf16 v[38:41], v[142:145], v[118:121], v[34:37]
	v_mfma_f32_16x16x32_bf16 v[46:49], v[70:73], v[122:125], v[66:69]
	v_mfma_f32_16x16x32_bf16 v[54:57], v[130:133], v[122:125], v[26:29]
	v_mfma_f32_16x16x32_bf16 v[62:65], v[134:137], v[122:125], v[74:77]
	v_mfma_f32_16x16x32_bf16 v[58:61], v[142:145], v[122:125], v[78:81]
	v_mfma_f32_16x16x32_bf16 v[50:53], v[70:73], v[126:129], v[90:93]
	v_mfma_f32_16x16x32_bf16 v[42:45], v[130:133], v[126:129], v[10:13]
	v_mfma_f32_16x16x32_bf16 v[34:37], v[134:137], v[126:129], v[6:9]
	v_mfma_f32_16x16x32_bf16 v[26:29], v[142:145], v[126:129], v[2:5]
	s_setprio 0
	v_add_u32_e32 v80, s8, v88
	s_nop 0
	v_or_b32_e32 v2, s6, v89
	v_ashrrev_i32_e32 v81, 31, v80
	v_readlane_b32 s40, v214, 50
	v_ashrrev_i32_e32 v3, 31, v2
	v_lshlrev_b64 v[4:5], 11, v[80:81]
	v_readlane_b32 s50, v214, 60
	v_readlane_b32 s51, v214, 61
	v_readlane_b32 s52, v214, 62
	v_readlane_b32 s53, v214, 63
	v_lshl_add_u64 v[6:7], s[50:51], 0, v[4:5]
	v_lshlrev_b64 v[66:67], 1, v[2:3]
	v_lshl_add_u64 v[4:5], s[52:53], 0, v[4:5]
	v_lshl_add_u64 v[68:69], v[4:5], 0, v[66:67]
	s_waitcnt vmcnt(0)
	s_barrier
	global_load_dwordx2 v[4:5], v[68:69], off
	v_lshl_add_u64 v[72:73], v[6:7], 0, v[66:67]
	global_load_dwordx2 v[228:229], v[72:73], off
	global_load_dwordx2 v[230:231], v[72:73], off offset:32
	global_load_dwordx2 v[232:233], v[68:69], off offset:32
	global_load_dwordx2 v[234:235], v[72:73], off offset:64
	global_load_dwordx2 v[236:237], v[68:69], off offset:64
	global_load_dwordx2 v[238:239], v[72:73], off offset:96
	global_load_dwordx2 v[240:241], v[68:69], off offset:96
	v_lshlrev_b64 v[70:71], 10, v[80:81]
	v_readlane_b32 s41, v214, 51
	v_readlane_b32 s42, v214, 52
	v_readlane_b32 s43, v214, 53
	v_readlane_b32 s44, v214, 54
	v_readlane_b32 s45, v214, 55
	v_readlane_b32 s46, v214, 56
	v_readlane_b32 s47, v214, 57
	v_readlane_b32 s48, v214, 58
	v_readlane_b32 s49, v214, 59
	v_readlane_b32 s54, v213, 0
	s_lshl_b64 s[8:9], s[8:9], 11
	v_readlane_b32 s55, v213, 1
	s_add_u32 s12, s54, s8
	s_addc_u32 s13, s55, s9
	s_lshl_b64 s[10:11], s[10:11], 11
	s_waitcnt vmcnt(7)
	v_lshlrev_b32_e32 v0, 16, v4
	v_rcp_f32_e32 v8, v0
	v_and_b32_e32 v0, 0xffff0000, v4
	v_rcp_f32_e32 v9, v0
	v_lshlrev_b32_e32 v0, 16, v5
	v_rcp_f32_e32 v4, v0
	v_and_b32_e32 v0, 0xffff0000, v5
	v_rcp_f32_e32 v5, v0
	s_waitcnt vmcnt(6)
	v_lshlrev_b32_e32 v6, 16, v228
	v_and_b32_e32 v7, 0xffff0000, v228
	v_lshlrev_b32_e32 v2, 16, v229
	v_and_b32_e32 v3, 0xffff0000, v229
	v_pk_mul_f32 v[6:7], v[8:9], v[6:7]
	v_pk_mul_f32 v[2:3], v[4:5], v[2:3]
	s_nop 0
	v_pk_mul_f32 v[4:5], v[84:85], v[2:3]
	v_pk_mul_f32 v[2:3], v[82:83], v[6:7]
	s_waitcnt vmcnt(5)
	v_lshlrev_b32_e32 v10, 16, v230
	s_waitcnt vmcnt(4)
	v_lshlrev_b32_e32 v0, 16, v232
	v_rcp_f32_e32 v12, v0
	v_and_b32_e32 v0, 0xffff0000, v232
	v_rcp_f32_e32 v13, v0
	v_lshlrev_b32_e32 v0, 16, v233
	v_rcp_f32_e32 v8, v0
	v_and_b32_e32 v0, 0xffff0000, v233
	v_rcp_f32_e32 v9, v0
	v_and_b32_e32 v11, 0xffff0000, v230
	v_lshlrev_b32_e32 v6, 16, v231
	v_and_b32_e32 v7, 0xffff0000, v231
	v_pk_mul_f32 v[10:11], v[12:13], v[10:11]
	v_pk_mul_f32 v[6:7], v[8:9], v[6:7]
	s_nop 0
	v_pk_mul_f32 v[8:9], v[96:97], v[6:7]
	v_pk_mul_f32 v[6:7], v[94:95], v[10:11]
	v_mov_b32_e32 v96, v141
	s_waitcnt vmcnt(3)
; __device__ __forceinline__ float bf_lo(unsigned u) { return __uint_as_float(u << 16); }
; __device__ __forceinline__ float bf_hi(unsigned u) { return __uint_as_float(u & 0xffff0000u); }
; __device__ __forceinline__ float frcp(float x) { return __builtin_amdgcn_rcpf(x); }
; __device__ void phaseC1(const Params& p, int l, char* smem) {
;     ...
; #pragma unroll
;         for (int i = 0; i < 4; ++i) {
;             const size_t row = (size_t)(m0 + wr * 64 + i * 16 + r);
; #pragma unroll
;             for (int j = 0; j < 4; ++j) {
;                 const int col = n0 + wc * 64 + j * 16 + g4 * 4;
;                 const uint2 gm = *(const uint2*)(p.gmb + row * 1024 + col);
;                 const uint2 ga = *(const uint2*)(p.gab + row * 1024 + col);
;                 acc[i][j][0] *= bf_lo(gm.x) * frcp(bf_lo(ga.x)); acc[i][j][1] *= bf_hi(gm.x) * frcp(bf_hi(ga.x));
;                 acc[i][j][2] *= bf_lo(gm.y) * frcp(bf_lo(ga.y)); acc[i][j][3] *= bf_hi(gm.y) * frcp(bf_hi(ga.y));
;             }
;         }
	v_lshlrev_b32_e32 v74, 16, v234
	s_waitcnt vmcnt(2)
	v_lshlrev_b32_e32 v0, 16, v236
	v_rcp_f32_e32 v76, v0
	v_and_b32_e32 v0, 0xffff0000, v236
	v_rcp_f32_e32 v77, v0
	v_lshlrev_b32_e32 v0, 16, v237
	v_rcp_f32_e32 v12, v0
	v_and_b32_e32 v0, 0xffff0000, v237
	v_rcp_f32_e32 v13, v0
	v_and_b32_e32 v75, 0xffff0000, v234
	v_lshlrev_b32_e32 v10, 16, v235
	v_and_b32_e32 v11, 0xffff0000, v235
	v_pk_mul_f32 v[74:75], v[76:77], v[74:75]
	v_pk_mul_f32 v[10:11], v[12:13], v[10:11]
	s_nop 0
	v_pk_mul_f32 v[12:13], v[100:101], v[10:11]
	v_pk_mul_f32 v[10:11], v[98:99], v[74:75]
	s_nop 0
	s_waitcnt vmcnt(1)
	v_lshlrev_b32_e32 v76, 16, v238
	s_waitcnt vmcnt(0)
	v_lshlrev_b32_e32 v0, 16, v240
	v_rcp_f32_e32 v78, v0
	v_and_b32_e32 v0, 0xffff0000, v240
	v_rcp_f32_e32 v79, v0
	v_lshlrev_b32_e32 v0, 16, v241
	v_rcp_f32_e32 v74, v0
	v_and_b32_e32 v0, 0xffff0000, v241
	v_rcp_f32_e32 v75, v0
	v_and_b32_e32 v77, 0xffff0000, v238
	v_lshlrev_b32_e32 v72, 16, v239
	v_and_b32_e32 v73, 0xffff0000, v239
	v_pk_mul_f32 v[72:73], v[74:75], v[72:73]
	v_pk_mul_f32 v[76:77], v[78:79], v[76:77]
	v_pk_mul_f32 v[16:17], v[16:17], v[72:73]
	v_or_b32_e32 v72, 16, v80
	v_ashrrev_i32_e32 v73, 31, v72
	v_lshlrev_b64 v[74:75], 10, v[72:73]
	v_lshlrev_b64 v[72:73], 11, v[72:73]
	v_pk_mul_f32 v[14:15], v[14:15], v[76:77]
	v_lshl_add_u64 v[76:77], s[50:51], 0, v[72:73]
	v_lshl_add_u64 v[72:73], s[52:53], 0, v[72:73]
	v_lshl_add_u64 v[72:73], v[72:73], 0, v[66:67]
	global_load_dwordx2 v[82:83], v[72:73], off
	v_lshl_add_u64 v[76:77], v[76:77], 0, v[66:67]
	global_load_dwordx2 v[228:229], v[76:77], off
	global_load_dwordx2 v[230:231], v[76:77], off offset:32
	global_load_dwordx2 v[232:233], v[72:73], off offset:32
	global_load_dwordx2 v[234:235], v[76:77], off offset:64
	global_load_dwordx2 v[236:237], v[72:73], off offset:64
	global_load_dwordx2 v[238:239], v[76:77], off offset:96
	global_load_dwordx2 v[240:241], v[72:73], off offset:96
	s_waitcnt vmcnt(7)
	v_lshlrev_b32_e32 v0, 16, v82
	v_rcp_f32_e32 v86, v0
	v_and_b32_e32 v0, 0xffff0000, v82
	v_rcp_f32_e32 v87, v0
	v_lshlrev_b32_e32 v0, 16, v83
	v_rcp_f32_e32 v82, v0
	v_and_b32_e32 v0, 0xffff0000, v83
	v_rcp_f32_e32 v83, v0
	s_waitcnt vmcnt(6)
	v_lshlrev_b32_e32 v84, 16, v228
	v_and_b32_e32 v85, 0xffff0000, v228
	v_lshlrev_b32_e32 v78, 16, v229
	v_and_b32_e32 v79, 0xffff0000, v229
	v_pk_mul_f32 v[78:79], v[82:83], v[78:79]
	v_pk_mul_f32 v[84:85], v[86:87], v[84:85]
	v_pk_mul_f32 v[20:21], v[20:21], v[78:79]
	v_pk_mul_f32 v[18:19], v[18:19], v[84:85]
	s_waitcnt vmcnt(5)
	v_lshlrev_b32_e32 v84, 16, v230
	s_waitcnt vmcnt(4)
	v_lshlrev_b32_e32 v0, 16, v232
	v_rcp_f32_e32 v86, v0
	v_and_b32_e32 v0, 0xffff0000, v232
	v_rcp_f32_e32 v87, v0
	v_lshlrev_b32_e32 v0, 16, v233
	v_rcp_f32_e32 v82, v0
	v_and_b32_e32 v0, 0xffff0000, v233
	v_rcp_f32_e32 v83, v0
	v_and_b32_e32 v85, 0xffff0000, v230
	v_lshlrev_b32_e32 v78, 16, v231
	v_and_b32_e32 v79, 0xffff0000, v231
	v_pk_mul_f32 v[78:79], v[82:83], v[78:79]
	v_pk_mul_f32 v[84:85], v[86:87], v[84:85]
	v_pk_mul_f32 v[24:25], v[24:25], v[78:79]
	v_pk_mul_f32 v[22:23], v[22:23], v[84:85]
	s_waitcnt vmcnt(3)
	v_lshlrev_b32_e32 v84, 16, v234
	s_waitcnt vmcnt(2)
	v_lshlrev_b32_e32 v0, 16, v236
	v_rcp_f32_e32 v86, v0
	v_and_b32_e32 v0, 0xffff0000, v236
	v_rcp_f32_e32 v87, v0
	v_lshlrev_b32_e32 v0, 16, v237
	v_rcp_f32_e32 v82, v0
	v_and_b32_e32 v0, 0xffff0000, v237
	v_rcp_f32_e32 v83, v0
	v_and_b32_e32 v85, 0xffff0000, v234
	v_lshlrev_b32_e32 v78, 16, v235
	v_and_b32_e32 v79, 0xffff0000, v235
	v_pk_mul_f32 v[78:79], v[82:83], v[78:79]
	v_pk_mul_f32 v[84:85], v[86:87], v[84:85]
	v_pk_mul_f32 v[32:33], v[32:33], v[78:79]
	s_nop 0
	v_pk_mul_f32 v[30:31], v[30:31], v[84:85]
	s_waitcnt vmcnt(1)
	v_lshlrev_b32_e32 v82, 16, v238
	s_waitcnt vmcnt(0)
	v_lshlrev_b32_e32 v0, 16, v240
	v_rcp_f32_e32 v84, v0
	v_and_b32_e32 v0, 0xffff0000, v240
	v_rcp_f32_e32 v85, v0
	v_lshlrev_b32_e32 v0, 16, v241
	v_rcp_f32_e32 v78, v0
	v_and_b32_e32 v0, 0xffff0000, v241
	v_rcp_f32_e32 v79, v0
	v_and_b32_e32 v83, 0xffff0000, v238
	v_lshlrev_b32_e32 v76, 16, v239
	v_and_b32_e32 v77, 0xffff0000, v239
	v_pk_mul_f32 v[76:77], v[78:79], v[76:77]
	v_pk_mul_f32 v[82:83], v[84:85], v[82:83]
	v_pk_mul_f32 v[40:41], v[40:41], v[76:77]
	v_or_b32_e32 v76, 32, v80
	v_ashrrev_i32_e32 v77, 31, v76
	v_lshlrev_b64 v[78:79], 10, v[76:77]
	v_lshlrev_b64 v[76:77], 11, v[76:77]
	v_pk_mul_f32 v[38:39], v[38:39], v[82:83]
	v_lshl_add_u64 v[82:83], s[50:51], 0, v[76:77]
	v_lshl_add_u64 v[76:77], s[52:53], 0, v[76:77]
	v_lshl_add_u64 v[76:77], v[76:77], 0, v[66:67]
	global_load_dwordx2 v[86:87], v[76:77], off
	v_lshl_add_u64 v[82:83], v[82:83], 0, v[66:67]
	global_load_dwordx2 v[228:229], v[82:83], off
	global_load_dwordx2 v[230:231], v[82:83], off offset:32
	global_load_dwordx2 v[232:233], v[76:77], off offset:32
	global_load_dwordx2 v[234:235], v[82:83], off offset:64
	global_load_dwordx2 v[236:237], v[76:77], off offset:64
	global_load_dwordx2 v[238:239], v[82:83], off offset:96
	global_load_dwordx2 v[240:241], v[76:77], off offset:96
	v_or_b32_e32 v80, 48, v80
	v_ashrrev_i32_e32 v81, 31, v80
	s_waitcnt vmcnt(7)
	v_lshlrev_b32_e32 v0, 16, v86
	v_rcp_f32_e32 v92, v0
	v_and_b32_e32 v0, 0xffff0000, v86
	v_rcp_f32_e32 v93, v0
	v_lshlrev_b32_e32 v0, 16, v87
	v_rcp_f32_e32 v86, v0
	v_and_b32_e32 v0, 0xffff0000, v87
	v_rcp_f32_e32 v87, v0
	s_waitcnt vmcnt(6)
	v_lshlrev_b32_e32 v90, 16, v228
	v_and_b32_e32 v91, 0xffff0000, v228
	v_lshlrev_b32_e32 v84, 16, v229
	v_and_b32_e32 v85, 0xffff0000, v229
	v_pk_mul_f32 v[84:85], v[86:87], v[84:85]
	v_pk_mul_f32 v[90:91], v[92:93], v[90:91]
	v_pk_mul_f32 v[48:49], v[48:49], v[84:85]
	v_pk_mul_f32 v[46:47], v[46:47], v[90:91]
	s_waitcnt vmcnt(5)
; __device__ __forceinline__ float bf_lo(unsigned u) { return __uint_as_float(u << 16); }
; __device__ __forceinline__ float bf_hi(unsigned u) { return __uint_as_float(u & 0xffff0000u); }
; __device__ __forceinline__ float frcp(float x) { return __builtin_amdgcn_rcpf(x); }
; __device__ void phaseC1(const Params& p, int l, char* smem) {
;     ...
; #pragma unroll
;         for (int i = 0; i < 4; ++i) {
;             const size_t row = (size_t)(m0 + wr * 64 + i * 16 + r);
; #pragma unroll
;             for (int j = 0; j < 4; ++j) {
;                 const int col = n0 + wc * 64 + j * 16 + g4 * 4;
;                 const uint2 gm = *(const uint2*)(p.gmb + row * 1024 + col);
;                 const uint2 ga = *(const uint2*)(p.gab + row * 1024 + col);
;                 acc[i][j][0] *= bf_lo(gm.x) * frcp(bf_lo(ga.x)); acc[i][j][1] *= bf_hi(gm.x) * frcp(bf_hi(ga.x));
;                 acc[i][j][2] *= bf_lo(gm.y) * frcp(bf_lo(ga.y)); acc[i][j][3] *= bf_hi(gm.y) * frcp(bf_hi(ga.y));
;             }
;         }
	v_lshlrev_b32_e32 v90, 16, v230
	s_waitcnt vmcnt(4)
	v_lshlrev_b32_e32 v0, 16, v232
	v_rcp_f32_e32 v92, v0
	v_and_b32_e32 v0, 0xffff0000, v232
	v_rcp_f32_e32 v93, v0
	v_lshlrev_b32_e32 v0, 16, v233
	v_rcp_f32_e32 v86, v0
	v_and_b32_e32 v0, 0xffff0000, v233
	v_rcp_f32_e32 v87, v0
	v_and_b32_e32 v91, 0xffff0000, v230
	v_lshlrev_b32_e32 v84, 16, v231
	v_and_b32_e32 v85, 0xffff0000, v231
	v_pk_mul_f32 v[84:85], v[86:87], v[84:85]
	v_pk_mul_f32 v[90:91], v[92:93], v[90:91]
	v_pk_mul_f32 v[56:57], v[56:57], v[84:85]
	v_pk_mul_f32 v[54:55], v[54:55], v[90:91]
	s_waitcnt vmcnt(3)
	v_lshlrev_b32_e32 v90, 16, v234
	s_waitcnt vmcnt(2)
	v_lshlrev_b32_e32 v0, 16, v236
	v_rcp_f32_e32 v92, v0
	v_and_b32_e32 v0, 0xffff0000, v236
	v_rcp_f32_e32 v93, v0
	v_lshlrev_b32_e32 v0, 16, v237
	v_rcp_f32_e32 v86, v0
	v_and_b32_e32 v0, 0xffff0000, v237
	v_rcp_f32_e32 v87, v0
	v_and_b32_e32 v91, 0xffff0000, v234
	v_lshlrev_b32_e32 v84, 16, v235
	v_and_b32_e32 v85, 0xffff0000, v235
	v_pk_mul_f32 v[84:85], v[86:87], v[84:85]
	v_pk_mul_f32 v[90:91], v[92:93], v[90:91]
	v_pk_mul_f32 v[64:65], v[64:65], v[84:85]
	s_nop 0
	v_pk_mul_f32 v[62:63], v[62:63], v[90:91]
	s_waitcnt vmcnt(1)
	v_lshlrev_b32_e32 v86, 16, v238
	s_waitcnt vmcnt(0)
	v_lshlrev_b32_e32 v0, 16, v240
	v_rcp_f32_e32 v90, v0
	v_and_b32_e32 v0, 0xffff0000, v240
	v_rcp_f32_e32 v91, v0
	v_lshlrev_b32_e32 v0, 16, v241
	v_rcp_f32_e32 v84, v0
	v_and_b32_e32 v0, 0xffff0000, v241
	v_rcp_f32_e32 v85, v0
	v_and_b32_e32 v87, 0xffff0000, v238
	v_lshlrev_b32_e32 v82, 16, v239
	v_and_b32_e32 v83, 0xffff0000, v239
	v_pk_mul_f32 v[82:83], v[84:85], v[82:83]
	v_pk_mul_f32 v[86:87], v[90:91], v[86:87]
	v_pk_mul_f32 v[60:61], v[60:61], v[82:83]
	v_lshlrev_b64 v[82:83], 10, v[80:81]
	v_lshlrev_b64 v[80:81], 11, v[80:81]
	v_lshl_add_u64 v[84:85], s[50:51], 0, v[80:81]
	v_lshl_add_u64 v[80:81], s[52:53], 0, v[80:81]
	v_lshl_add_u64 v[80:81], v[80:81], 0, v[66:67]
	global_load_dwordx2 v[90:91], v[80:81], off
	v_lshl_add_u64 v[84:85], v[84:85], 0, v[66:67]
	v_pk_mul_f32 v[58:59], v[58:59], v[86:87]
	global_load_dwordx2 v[228:229], v[84:85], off
	global_load_dwordx2 v[230:231], v[84:85], off offset:32
	global_load_dwordx2 v[232:233], v[80:81], off offset:32
	global_load_dwordx2 v[234:235], v[84:85], off offset:64
	global_load_dwordx2 v[236:237], v[80:81], off offset:64
	global_load_dwordx2 v[238:239], v[84:85], off offset:96
	global_load_dwordx2 v[240:241], v[80:81], off offset:96
	v_readlane_b32 s36, v214, 34
	v_readlane_b32 s38, v214, 36
	v_readlane_b32 s39, v214, 37
	s_add_u32 s10, s38, s10
	s_addc_u32 s11, s39, s11
	s_lshl_b64 s[6:7], s[6:7], 11
	v_readlane_b32 s37, v214, 35
	v_readlane_b32 s40, v214, 38
	v_readlane_b32 s41, v214, 39
	v_readlane_b32 s42, v214, 40
	v_readlane_b32 s43, v214, 41
	v_readlane_b32 s44, v214, 42
	v_readlane_b32 s45, v214, 43
	v_readlane_b32 s46, v214, 44
	v_readlane_b32 s47, v214, 45
	v_readlane_b32 s48, v214, 46
	v_readlane_b32 s49, v214, 47
	v_readlane_b32 s50, v214, 48
	v_readlane_b32 s51, v214, 49
	s_waitcnt vmcnt(7)
	v_lshlrev_b32_e32 v0, 16, v90
	v_rcp_f32_e32 v94, v0
	v_and_b32_e32 v0, 0xffff0000, v90
	v_rcp_f32_e32 v95, v0
	v_lshlrev_b32_e32 v0, 16, v91
	v_rcp_f32_e32 v90, v0
	v_and_b32_e32 v0, 0xffff0000, v91
	v_rcp_f32_e32 v91, v0
	s_waitcnt vmcnt(6)
	v_lshlrev_b32_e32 v92, 16, v228
	v_and_b32_e32 v93, 0xffff0000, v228
	v_lshlrev_b32_e32 v86, 16, v229
	v_and_b32_e32 v87, 0xffff0000, v229
	v_pk_mul_f32 v[86:87], v[90:91], v[86:87]
	v_pk_mul_f32 v[92:93], v[94:95], v[92:93]
	v_pk_mul_f32 v[52:53], v[52:53], v[86:87]
	v_pk_mul_f32 v[50:51], v[50:51], v[92:93]
	s_waitcnt vmcnt(5)
	v_lshlrev_b32_e32 v92, 16, v230
	s_waitcnt vmcnt(4)
	v_lshlrev_b32_e32 v0, 16, v232
	v_rcp_f32_e32 v94, v0
	v_and_b32_e32 v0, 0xffff0000, v232
	v_rcp_f32_e32 v95, v0
	v_lshlrev_b32_e32 v0, 16, v233
	v_rcp_f32_e32 v90, v0
	v_and_b32_e32 v0, 0xffff0000, v233
	v_rcp_f32_e32 v91, v0
	v_and_b32_e32 v93, 0xffff0000, v230
	v_lshlrev_b32_e32 v86, 16, v231
	v_and_b32_e32 v87, 0xffff0000, v231
	v_pk_mul_f32 v[86:87], v[90:91], v[86:87]
	v_pk_mul_f32 v[92:93], v[94:95], v[92:93]
	v_pk_mul_f32 v[44:45], v[44:45], v[86:87]
	v_pk_mul_f32 v[42:43], v[42:43], v[92:93]
	s_waitcnt vmcnt(3)
	v_lshlrev_b32_e32 v92, 16, v234
	s_waitcnt vmcnt(2)
	v_lshlrev_b32_e32 v0, 16, v236
	v_rcp_f32_e32 v94, v0
	v_and_b32_e32 v0, 0xffff0000, v236
	v_rcp_f32_e32 v95, v0
	v_lshlrev_b32_e32 v0, 16, v237
	v_rcp_f32_e32 v90, v0
	v_and_b32_e32 v0, 0xffff0000, v237
	v_rcp_f32_e32 v91, v0
	v_and_b32_e32 v93, 0xffff0000, v234
	v_lshlrev_b32_e32 v86, 16, v235
	v_and_b32_e32 v87, 0xffff0000, v235
	v_pk_mul_f32 v[86:87], v[90:91], v[86:87]
	v_pk_mul_f32 v[92:93], v[94:95], v[92:93]
	v_pk_mul_f32 v[36:37], v[36:37], v[86:87]
	s_nop 0
	v_pk_mul_f32 v[34:35], v[34:35], v[92:93]
	s_waitcnt vmcnt(1)
	v_lshlrev_b32_e32 v90, 16, v238
	s_waitcnt vmcnt(0)
; __device__ __forceinline__ float bf_lo(unsigned u) { return __uint_as_float(u << 16); }
; __device__ __forceinline__ float bf_hi(unsigned u) { return __uint_as_float(u & 0xffff0000u); }
; __device__ __forceinline__ float frcp(float x) { return __builtin_amdgcn_rcpf(x); }
; template <int AMODE>
; __device__ __forceinline__ void gemm_kloop(f32x4 (&acc)[4][4], const u16* __restrict__ A, int lda,
;                                            const u16* __restrict__ Bt, int ldb, int K, char* smem,
;                                            const float* __restrict__ ssq_rows) {
;     ...
;     GLOAD(0, 0);
;     LSTORE(0);
;     asm volatile("s_waitcnt vmcnt(0)" ::: "memory");
;     __syncthreads();
;     for (int kt = 0; kt < nk; ++kt) {
; __device__ void phaseC1(const Params& p, int l, char* smem) {
;     ...
;                 acc[i][j][0] *= bf_lo(gm.x) * frcp(bf_lo(ga.x)); acc[i][j][1] *= bf_hi(gm.x) * frcp(bf_hi(ga.x));
;                 acc[i][j][2] *= bf_lo(gm.y) * frcp(bf_lo(ga.y)); acc[i][j][3] *= bf_hi(gm.y) * frcp(bf_hi(ga.y));
;             }
;         }
;         gemm_kloop<0>(acc, p.yab + (size_t)m0 * 1024, 1024, p.wt_a + ((size_t)l * 1024 + n0) * 1024, 1024, 1024, smem, nullptr);
	v_lshlrev_b32_e32 v0, 16, v240
	v_rcp_f32_e32 v92, v0
	v_and_b32_e32 v0, 0xffff0000, v240
	v_rcp_f32_e32 v93, v0
	v_lshlrev_b32_e32 v0, 16, v241
	v_rcp_f32_e32 v86, v0
	v_and_b32_e32 v0, 0xffff0000, v241
	v_rcp_f32_e32 v87, v0
	v_and_b32_e32 v91, 0xffff0000, v238
	v_lshlrev_b32_e32 v84, 16, v239
	v_and_b32_e32 v85, 0xffff0000, v239
	v_pk_mul_f32 v[84:85], v[86:87], v[84:85]
	v_ashrrev_i32_e32 v94, 6, v96
	v_bfe_u32 v0, v96, 3, 3
	v_pk_mul_f32 v[28:29], v[28:29], v[84:85]
	v_lshl_or_b32 v84, v94, 3, v0
	v_ashrrev_i32_e32 v85, 31, v84
	v_pk_mul_f32 v[90:91], v[92:93], v[90:91]
	v_bitop3_b32 v0, v0, v96, 7 bitop3:0x78
	v_lshlrev_b64 v[86:87], 11, v[84:85]
	v_pk_mul_f32 v[26:27], v[26:27], v[90:91]
	v_lshlrev_b32_e32 v0, 4, v0
	v_lshl_add_u64 v[90:91], s[10:11], 0, v[86:87]
	v_lshl_add_u64 v[92:93], v[90:91], 0, v[0:1]
	v_lshlrev_b32_e32 v90, 10, v94
	v_add_u32_e32 v91, 0x8000, v90
	v_lshl_add_u64 v[84:85], s[12:13], 0, v[86:87]
	v_readfirstlane_b32 s10, v91
	s_mov_b32 m0, s10
	v_readfirstlane_b32 s10, v90
	v_add_u32_e32 v91, 0x9000, v90
	v_lshl_add_u64 v[84:85], v[84:85], 0, v[0:1]
	global_load_lds_dwordx4 v[92:93], off
	s_mov_b32 m0, s10
	s_mov_b64 s[12:13], 0x10000
	v_readfirstlane_b32 s10, v91
	v_add_u32_e32 v91, 0x1000, v90
	global_load_lds_dwordx4 v[84:85], off
	v_lshl_add_u64 v[94:95], v[92:93], 0, s[12:13]
	s_mov_b32 m0, s10
	v_readfirstlane_b32 s10, v91
	v_add_u32_e32 v91, 0xa000, v90
	global_load_lds_dwordx4 v[94:95], off
	v_lshl_add_u64 v[94:95], v[84:85], 0, s[12:13]
	s_mov_b32 m0, s10
	s_mov_b64 s[12:13], 0x20000
	v_readfirstlane_b32 s10, v91
	v_add_u32_e32 v91, 0x2000, v90
	global_load_lds_dwordx4 v[94:95], off
	v_lshl_add_u64 v[94:95], v[92:93], 0, s[12:13]
	s_mov_b32 m0, s10
	v_readfirstlane_b32 s10, v91
	v_add_u32_e32 v91, 0xb000, v90
	global_load_lds_dwordx4 v[94:95], off
	v_lshl_add_u64 v[94:95], v[84:85], 0, s[12:13]
	s_mov_b32 m0, s10
	s_mov_b64 s[12:13], 0x30000
	v_readfirstlane_b32 s10, v91
	v_add_u32_e32 v91, 0x3000, v90
	global_load_lds_dwordx4 v[94:95], off
	v_lshl_add_u64 v[92:93], v[92:93], 0, s[12:13]
	s_mov_b32 m0, s10
	v_readfirstlane_b32 s10, v91
	global_load_lds_dwordx4 v[92:93], off
	v_lshl_add_u64 v[84:85], v[84:85], 0, s[12:13]
	s_mov_b32 m0, s10
	v_lshrrev_b32_e32 v91, 1, v96
	global_load_lds_dwordx4 v[84:85], off
	v_and_b32_e32 v85, 15, v96
	s_mov_b32 s10, 0x1ffffc0
	v_and_or_b32 v85, v91, s10, v85
	v_and_b32_e32 v97, 7, v96
	v_bfe_u32 v84, v96, 4, 2
	v_lshlrev_b32_e32 v92, 7, v85
	v_lshlrev_b32_e32 v85, 7, v96
	v_and_b32_e32 v91, 0x2780, v85
	v_bitop3_b32 v85, v84, v96, 7 bitop3:0x78
	v_bitop3_b32 v84, v84, v97, 4 bitop3:0x36
	s_waitcnt vmcnt(0)
	v_lshlrev_b32_e32 v94, 4, v85
	v_lshlrev_b32_e32 v93, 4, v84
	v_lshl_add_u64 v[84:85], s[6:7], 0, v[86:87]
	v_lshl_add_u64 v[86:87], s[8:9], 0, v[86:87]
	v_or_b32_e32 v84, v84, v0
	v_or_b32_e32 v86, v86, v0
	v_lshl_add_u64 v[84:85], s[4:5], 0, v[84:85]
	v_lshl_add_u64 v[86:87], s[54:55], 0, v[86:87]
	s_mov_b64 s[6:7], 0
	s_mov_b32 s8, 0
	s_waitcnt vmcnt(0) lgkmcnt(0)
	s_barrier
.LBB0_709:
	s_and_b32 s9, s8, 0x4000
	s_xor_b32 s10, s9, 0x4000
	v_add_u32_e32 v0, s10, v90
	v_add_u32_e32 v95, 0x8000, v0
	v_lshl_add_u64 v[96:97], v[84:85], 0, s[6:7]
	v_readfirstlane_b32 s10, v95
	v_lshl_add_u64 v[98:99], v[96:97], 0, s[62:63]
	v_lshl_add_u64 v[100:101], v[86:87], 0, s[6:7]
	s_mov_b32 m0, s10
	v_readfirstlane_b32 s10, v0
	v_add_u32_e32 v95, 0x9000, v0
	v_lshl_add_u64 v[102:103], v[100:101], 0, s[62:63]
	global_load_lds_dwordx4 v[98:99], off
	s_mov_b32 m0, s10
	v_readfirstlane_b32 s10, v95
	v_add_u32_e32 v95, 0x1000, v0
	global_load_lds_dwordx4 v[102:103], off
	v_lshl_add_u64 v[98:99], v[96:97], 0, s[68:69]
	s_mov_b32 m0, s10
	v_readfirstlane_b32 s10, v95
	v_add_u32_e32 v95, 0xa000, v0
	global_load_lds_dwordx4 v[98:99], off
	v_lshl_add_u64 v[98:99], v[100:101], 0, s[68:69]
	s_mov_b32 m0, s10
	v_readfirstlane_b32 s10, v95
	v_add_u32_e32 v95, 0x2000, v0
	global_load_lds_dwordx4 v[98:99], off
	v_lshl_add_u64 v[98:99], v[96:97], 0, s[64:65]
	s_mov_b32 m0, s10
	v_readfirstlane_b32 s10, v95
	v_add_u32_e32 v95, 0xb000, v0
	global_load_lds_dwordx4 v[98:99], off
	v_lshl_add_u64 v[98:99], v[100:101], 0, s[64:65]
	s_mov_b32 m0, s10
	v_readfirstlane_b32 s10, v95
	v_add_u32_e32 v0, 0x3000, v0
	global_load_lds_dwordx4 v[98:99], off
	v_lshl_add_u64 v[96:97], v[96:97], 0, s[66:67]
	s_mov_b32 m0, s10
	v_readfirstlane_b32 s10, v0
	global_load_lds_dwordx4 v[96:97], off
	v_lshl_add_u64 v[96:97], v[100:101], 0, s[66:67]
	s_mov_b32 m0, s10
	v_add_u32_e32 v0, s9, v92
	global_load_lds_dwordx4 v[96:97], off
	v_or_b32_e32 v95, s9, v91
	v_add_u32_e32 v114, v0, v94
	v_add_u32_e32 v130, v95, v94
	v_add_u32_e32 v0, v0, v93
	ds_read_b128 v[96:99], v114
	ds_read_b128 v[100:103], v114 offset:2048
	ds_read_b128 v[110:113], v114 offset:4096
	ds_read_b128 v[114:117], v114 offset:6144
	ds_read_b128 v[118:121], v130 offset:32768
	ds_read_b128 v[122:125], v130 offset:34816
	ds_read_b128 v[126:129], v130 offset:36864
	ds_read_b128 v[130:133], v130 offset:38912
	ds_read_b128 v[134:137], v0
	ds_read_b128 v[142:145], v0 offset:2048
	ds_read_b128 v[146:149], v0 offset:4096
	ds_read_b128 v[150:153], v0 offset:6144
	v_add_u32_e32 v0, v95, v93
	ds_read_b128 v[172:175], v0 offset:32768
	ds_read_b128 v[176:179], v0 offset:34816
	ds_read_b128 v[180:183], v0 offset:36864
	ds_read_b128 v[184:187], v0 offset:38912
	s_setprio 1
	s_waitcnt lgkmcnt(0)
; #define MFMA(a, b, c) __builtin_amdgcn_mfma_f32_16x16x32_bf16((a), (b), (c), 0, 0, 0)
; template <int AMODE>
; __device__ __forceinline__ void gemm_kloop(f32x4 (&acc)[4][4], const u16* __restrict__ A, int lda,
;                                            const u16* __restrict__ Bt, int ldb, int K, char* smem,
;                                            const float* __restrict__ ssq_rows) {
;     ...
;     for (int kt = 0; kt < nk; ++kt) {
;         const int buf = kt & 1;
;         if (kt + 1 < nk) GLOAD(kt + 1, buf ^ 1);
;         const char* ab = As + buf * 16384 + (wr * 64 + r) * 128;
;         const char* bb = Bs + buf * 16384 + (wc * 64 + r) * 128;
;         bf16x8 af[2][4], bfr[2][4];
; #pragma unroll
;         for (int ks = 0; ks < 2; ++ks) {
;             const int co = ((ks * 4 + g4) ^ (r & 7)) << 4;
; #pragma unroll
;             for (int i = 0; i < 4; ++i) af[ks][i] = ld_frag(ab + i * 2048 + co);
; #pragma unroll
;             for (int j = 0; j < 4; ++j) bfr[ks][j] = ld_frag(bb + j * 2048 + co);
;         }
;         __builtin_amdgcn_sched_barrier(0);
;         __builtin_amdgcn_s_setprio(1);
; #pragma unroll
;         for (int ks = 0; ks < 2; ++ks)
; #pragma unroll
;             for (int i = 0; i < 4; ++i)
; #pragma unroll
;                 for (int j = 0; j < 4; ++j) acc[i][j] = MFMA(bfr[ks][j], af[ks][i], acc[i][j]);
;         __builtin_amdgcn_s_setprio(0);
;         __builtin_amdgcn_sched_barrier(0);
;         if (kt + 1 < nk) LSTORE(buf ^ 1);
;         asm volatile("s_waitcnt vmcnt(0)" ::: "memory");
;         __syncthreads();
;     }
	v_mfma_f32_16x16x32_bf16 v[2:5], v[118:121], v[96:99], v[2:5]
	v_mfma_f32_16x16x32_bf16 v[6:9], v[122:125], v[96:99], v[6:9]
	v_mfma_f32_16x16x32_bf16 v[10:13], v[126:129], v[96:99], v[10:13]
	v_mfma_f32_16x16x32_bf16 v[14:17], v[130:133], v[96:99], v[14:17]
	v_mfma_f32_16x16x32_bf16 v[18:21], v[118:121], v[100:103], v[18:21]
	v_mfma_f32_16x16x32_bf16 v[22:25], v[122:125], v[100:103], v[22:25]
	v_mfma_f32_16x16x32_bf16 v[30:33], v[126:129], v[100:103], v[30:33]
	v_mfma_f32_16x16x32_bf16 v[38:41], v[130:133], v[100:103], v[38:41]
	v_mfma_f32_16x16x32_bf16 v[46:49], v[118:121], v[110:113], v[46:49]
	v_mfma_f32_16x16x32_bf16 v[54:57], v[122:125], v[110:113], v[54:57]
	v_mfma_f32_16x16x32_bf16 v[62:65], v[126:129], v[110:113], v[62:65]
	v_mfma_f32_16x16x32_bf16 v[58:61], v[130:133], v[110:113], v[58:61]
	v_mfma_f32_16x16x32_bf16 v[50:53], v[118:121], v[114:117], v[50:53]
	v_mfma_f32_16x16x32_bf16 v[42:45], v[122:125], v[114:117], v[42:45]
	v_mfma_f32_16x16x32_bf16 v[34:37], v[126:129], v[114:117], v[34:37]
	v_mfma_f32_16x16x32_bf16 v[26:29], v[130:133], v[114:117], v[26:29]
	v_mfma_f32_16x16x32_bf16 v[2:5], v[172:175], v[134:137], v[2:5]
	v_mfma_f32_16x16x32_bf16 v[6:9], v[176:179], v[134:137], v[6:9]
	v_mfma_f32_16x16x32_bf16 v[10:13], v[180:183], v[134:137], v[10:13]
	v_mfma_f32_16x16x32_bf16 v[14:17], v[184:187], v[134:137], v[14:17]
	v_mfma_f32_16x16x32_bf16 v[18:21], v[172:175], v[142:145], v[18:21]
	v_mfma_f32_16x16x32_bf16 v[22:25], v[176:179], v[142:145], v[22:25]
	v_mfma_f32_16x16x32_bf16 v[30:33], v[180:183], v[142:145], v[30:33]
	v_mfma_f32_16x16x32_bf16 v[38:41], v[184:187], v[142:145], v[38:41]
	v_mfma_f32_16x16x32_bf16 v[46:49], v[172:175], v[146:149], v[46:49]
	v_mfma_f32_16x16x32_bf16 v[54:57], v[176:179], v[146:149], v[54:57]
	v_mfma_f32_16x16x32_bf16 v[62:65], v[180:183], v[146:149], v[62:65]
	v_mfma_f32_16x16x32_bf16 v[58:61], v[184:187], v[146:149], v[58:61]
	v_mfma_f32_16x16x32_bf16 v[50:53], v[172:175], v[150:153], v[50:53]
	v_mfma_f32_16x16x32_bf16 v[42:45], v[176:179], v[150:153], v[42:45]
	v_mfma_f32_16x16x32_bf16 v[34:37], v[180:183], v[150:153], v[34:37]
	v_mfma_f32_16x16x32_bf16 v[26:29], v[184:187], v[150:153], v[26:29]
	s_setprio 0
	s_waitcnt vmcnt(0)
	s_add_u32 s6, s6, 0x80
	s_addc_u32 s7, s7, 0
	s_addk_i32 s8, 0x4000
	s_cmpk_eq_i32 s6, 0x780
	s_waitcnt vmcnt(0)
	s_barrier
	s_cbranch_scc0 .LBB0_709
	v_add_u32_e32 v0, v92, v94
	ds_read_b128 v[84:87], v0 offset:16384
	ds_read_b128 v[96:99], v0 offset:18432
	ds_read_b128 v[100:103], v0 offset:20480
	ds_read_b128 v[110:113], v0 offset:22528
	v_add_u32_e32 v0, v91, v94
	ds_read_b128 v[114:117], v0 offset:49152
	ds_read_b128 v[118:121], v0 offset:51200
	ds_read_b128 v[122:125], v0 offset:53248
	ds_read_b128 v[126:129], v0 offset:55296
	v_add_u32_e32 v0, v92, v93
	ds_read_b128 v[130:133], v0 offset:16384
	ds_read_b128 v[134:137], v0 offset:18432
	ds_read_b128 v[142:145], v0 offset:20480
	ds_read_b128 v[146:149], v0 offset:22528
	v_add_u32_e32 v0, v91, v93
	ds_read_b128 v[90:93], v0 offset:49152
	ds_read_b128 v[150:153], v0 offset:51200
	ds_read_b128 v[172:175], v0 offset:53248
	ds_read_b128 v[176:179], v0 offset:55296
	s_setprio 1
	s_waitcnt lgkmcnt(11)
	v_mfma_f32_16x16x32_bf16 v[2:5], v[114:117], v[84:87], v[2:5]
	s_waitcnt lgkmcnt(10)
	v_mfma_f32_16x16x32_bf16 v[6:9], v[118:121], v[84:87], v[6:9]
	s_waitcnt lgkmcnt(9)
	v_mfma_f32_16x16x32_bf16 v[10:13], v[122:125], v[84:87], v[10:13]
	s_waitcnt lgkmcnt(8)
	v_mfma_f32_16x16x32_bf16 v[14:17], v[126:129], v[84:87], v[14:17]
	v_mfma_f32_16x16x32_bf16 v[18:21], v[114:117], v[96:99], v[18:21]
	v_mfma_f32_16x16x32_bf16 v[22:25], v[118:121], v[96:99], v[22:25]
	v_mfma_f32_16x16x32_bf16 v[30:33], v[122:125], v[96:99], v[30:33]
	v_mfma_f32_16x16x32_bf16 v[84:87], v[126:129], v[96:99], v[38:41]
	v_mfma_f32_16x16x32_bf16 v[46:49], v[114:117], v[100:103], v[46:49]
	v_mfma_f32_16x16x32_bf16 v[54:57], v[118:121], v[100:103], v[54:57]
	v_mfma_f32_16x16x32_bf16 v[62:65], v[122:125], v[100:103], v[62:65]
	v_mfma_f32_16x16x32_bf16 v[58:61], v[126:129], v[100:103], v[58:61]
	v_mfma_f32_16x16x32_bf16 v[50:53], v[114:117], v[110:113], v[50:53]
	v_mfma_f32_16x16x32_bf16 v[94:97], v[118:121], v[110:113], v[42:45]
	v_mfma_f32_16x16x32_bf16 v[98:101], v[122:125], v[110:113], v[34:37]
	v_mfma_f32_16x16x32_bf16 v[110:113], v[126:129], v[110:113], v[26:29]
	s_waitcnt lgkmcnt(3)
	v_mfma_f32_16x16x32_bf16 v[114:117], v[90:93], v[130:133], v[2:5]
	s_waitcnt lgkmcnt(2)
	v_mfma_f32_16x16x32_bf16 v[118:121], v[150:153], v[130:133], v[6:9]
	s_waitcnt lgkmcnt(1)
	v_mfma_f32_16x16x32_bf16 v[122:125], v[172:175], v[130:133], v[10:13]
	s_waitcnt lgkmcnt(0)
	v_mfma_f32_16x16x32_bf16 v[126:129], v[176:179], v[130:133], v[14:17]
	v_mfma_f32_16x16x32_bf16 v[130:133], v[90:93], v[134:137], v[18:21]
	v_mfma_f32_16x16x32_bf16 v[42:45], v[150:153], v[134:137], v[22:25]
	v_mfma_f32_16x16x32_bf16 v[38:41], v[172:175], v[134:137], v[30:33]
	v_mfma_f32_16x16x32_bf16 v[34:37], v[176:179], v[134:137], v[84:87]
	v_mfma_f32_16x16x32_bf16 v[30:33], v[90:93], v[142:145], v[46:49]
	v_mfma_f32_16x16x32_bf16 v[26:29], v[150:153], v[142:145], v[54:57]
	v_mfma_f32_16x16x32_bf16 v[22:25], v[172:175], v[142:145], v[62:65]
	v_mfma_f32_16x16x32_bf16 v[18:21], v[176:179], v[142:145], v[58:61]
	v_mfma_f32_16x16x32_bf16 v[14:17], v[90:93], v[146:149], v[50:53]
	v_mfma_f32_16x16x32_bf16 v[10:13], v[150:153], v[146:149], v[94:97]
	v_mfma_f32_16x16x32_bf16 v[6:9], v[172:175], v[146:149], v[98:101]
	v_mfma_f32_16x16x32_bf16 v[2:5], v[176:179], v[146:149], v[110:113]
	s_setprio 0
	s_waitcnt vmcnt(0)
	s_barrier
; __device__ __forceinline__ float bf_lo(unsigned u) { return __uint_as_float(u << 16); }
; __device__ __forceinline__ float bf_hi(unsigned u) { return __uint_as_float(u & 0xffff0000u); }
; __device__ void phaseC1(const Params& p, int l, char* smem) {
;     ...
; #pragma unroll
;         for (int i = 0; i < 4; ++i) {
;             const size_t row = (size_t)(m0 + wr * 64 + i * 16 + r);
; #pragma unroll
;             for (int j = 0; j < 4; ++j) {
;                 const int col = n0 + wc * 64 + j * 16 + g4 * 4;
;                 const uint2 ga = *(const uint2*)(p.gab + row * 1024 + col);
;                 *(uint2*)(p.ub + row * 1024 + col) =
;                     make_uint2(pk2(acc[i][j][0] * bf_lo(ga.x), acc[i][j][1] * bf_hi(ga.x)),
;                                pk2(acc[i][j][2] * bf_lo(ga.y), acc[i][j][3] * bf_hi(ga.y)));
;             }
;         }
	global_load_dwordx2 v[228:229], v[68:69], off
	global_load_dwordx2 v[230:231], v[68:69], off offset:32
	global_load_dwordx2 v[232:233], v[68:69], off offset:64
	global_load_dwordx2 v[234:235], v[68:69], off offset:96
	v_readlane_b32 s36, v213, 4
	v_readlane_b32 s37, v213, 5
	v_readlane_b32 s38, v213, 6
	v_readlane_b32 s39, v213, 7
	v_readlane_b32 s40, v213, 8
	v_readlane_b32 s41, v213, 9
	v_readlane_b32 s42, v213, 10
	v_readlane_b32 s43, v213, 11
	v_readlane_b32 s44, v213, 12
	v_readlane_b32 s45, v213, 13
	v_readlane_b32 s46, v213, 14
	v_readlane_b32 s47, v213, 15
	v_readlane_b32 s48, v213, 16
	v_readlane_b32 s49, v213, 17
	v_readlane_b32 s50, v213, 18
	v_readlane_b32 s51, v213, 19
	s_waitcnt vmcnt(3)
	v_lshlrev_b32_e32 v48, 16, v228
	v_and_b32_e32 v49, 0xffff0000, v228
	v_pk_mul_f32 v[48:49], v[114:115], v[48:49]
	s_nop 0
	v_cvt_pk_bf16_f32 v46, v48, v49
	v_lshlrev_b32_e32 v48, 16, v229
	v_and_b32_e32 v49, 0xffff0000, v229
	v_pk_mul_f32 v[48:49], v[116:117], v[48:49]
	s_nop 0
	v_cvt_pk_bf16_f32 v47, v48, v49
	v_lshl_add_u64 v[48:49], v[70:71], 1, s[36:37]
	v_lshl_add_u64 v[48:49], v[48:49], 0, v[66:67]
	global_store_dwordx2 v[48:49], v[46:47], off
	s_waitcnt vmcnt(3)
	v_lshlrev_b32_e32 v50, 16, v230
	v_and_b32_e32 v51, 0xffff0000, v230
	v_pk_mul_f32 v[50:51], v[118:119], v[50:51]
	s_nop 0
	v_cvt_pk_bf16_f32 v46, v50, v51
	v_lshlrev_b32_e32 v50, 16, v231
	v_and_b32_e32 v51, 0xffff0000, v231
	v_pk_mul_f32 v[50:51], v[120:121], v[50:51]
	s_nop 0
	v_cvt_pk_bf16_f32 v47, v50, v51
	global_store_dwordx2 v[48:49], v[46:47], off offset:32
	s_waitcnt vmcnt(3)
	v_lshlrev_b32_e32 v50, 16, v232
	v_and_b32_e32 v51, 0xffff0000, v232
	v_pk_mul_f32 v[50:51], v[122:123], v[50:51]
	s_nop 0
	v_cvt_pk_bf16_f32 v46, v50, v51
	v_lshlrev_b32_e32 v50, 16, v233
	v_and_b32_e32 v51, 0xffff0000, v233
	v_pk_mul_f32 v[50:51], v[124:125], v[50:51]
	s_nop 0
	v_cvt_pk_bf16_f32 v47, v50, v51
	global_store_dwordx2 v[48:49], v[46:47], off offset:64
	s_waitcnt vmcnt(3)
	v_lshlrev_b32_e32 v50, 16, v234
	v_and_b32_e32 v51, 0xffff0000, v234
	v_pk_mul_f32 v[50:51], v[126:127], v[50:51]
	s_nop 0
	v_cvt_pk_bf16_f32 v46, v50, v51
	v_lshlrev_b32_e32 v50, 16, v235
	v_and_b32_e32 v51, 0xffff0000, v235
	v_pk_mul_f32 v[50:51], v[128:129], v[50:51]
	s_nop 0
	v_cvt_pk_bf16_f32 v47, v50, v51
	global_store_dwordx2 v[48:49], v[46:47], off offset:96
	global_load_dwordx2 v[228:229], v[72:73], off
	global_load_dwordx2 v[230:231], v[72:73], off offset:32
	global_load_dwordx2 v[232:233], v[72:73], off offset:64
	global_load_dwordx2 v[234:235], v[72:73], off offset:96
	s_waitcnt vmcnt(3)
	v_lshlrev_b32_e32 v48, 16, v228
	v_and_b32_e32 v49, 0xffff0000, v228
	v_pk_mul_f32 v[48:49], v[130:131], v[48:49]
	s_nop 0
	v_cvt_pk_bf16_f32 v46, v48, v49
	v_lshlrev_b32_e32 v48, 16, v229
	v_and_b32_e32 v49, 0xffff0000, v229
	v_pk_mul_f32 v[48:49], v[132:133], v[48:49]
	s_nop 0
	v_cvt_pk_bf16_f32 v47, v48, v49
	v_lshl_add_u64 v[48:49], v[74:75], 1, s[36:37]
	v_lshl_add_u64 v[48:49], v[48:49], 0, v[66:67]
	global_store_dwordx2 v[48:49], v[46:47], off
	s_waitcnt vmcnt(3)
	v_lshlrev_b32_e32 v50, 16, v230
	v_and_b32_e32 v51, 0xffff0000, v230
	v_lshlrev_b32_e32 v46, 16, v231
	v_and_b32_e32 v47, 0xffff0000, v231
	v_pk_mul_f32 v[42:43], v[42:43], v[50:51]
	v_pk_mul_f32 v[44:45], v[44:45], v[46:47]
	v_cvt_pk_bf16_f32 v42, v42, v43
	v_cvt_pk_bf16_f32 v43, v44, v45
	global_store_dwordx2 v[48:49], v[42:43], off offset:32
	s_waitcnt vmcnt(3)
	v_lshlrev_b32_e32 v44, 16, v232
	v_and_b32_e32 v45, 0xffff0000, v232
	v_lshlrev_b32_e32 v42, 16, v233
	v_and_b32_e32 v43, 0xffff0000, v233
	v_pk_mul_f32 v[38:39], v[38:39], v[44:45]
	v_pk_mul_f32 v[40:41], v[40:41], v[42:43]
	v_cvt_pk_bf16_f32 v38, v38, v39
	v_cvt_pk_bf16_f32 v39, v40, v41
	global_store_dwordx2 v[48:49], v[38:39], off offset:64
	s_waitcnt vmcnt(3)
; __device__ __forceinline__ float bf_lo(unsigned u) { return __uint_as_float(u << 16); }
; __device__ __forceinline__ float bf_hi(unsigned u) { return __uint_as_float(u & 0xffff0000u); }
; __device__ void phaseC1(const Params& p, int l, char* smem) {
;     ...
; #pragma unroll
;         for (int i = 0; i < 4; ++i) {
;             const size_t row = (size_t)(m0 + wr * 64 + i * 16 + r);
; #pragma unroll
;             for (int j = 0; j < 4; ++j) {
;                 const int col = n0 + wc * 64 + j * 16 + g4 * 4;
;                 const uint2 ga = *(const uint2*)(p.gab + row * 1024 + col);
;                 *(uint2*)(p.ub + row * 1024 + col) =
;                     make_uint2(pk2(acc[i][j][0] * bf_lo(ga.x), acc[i][j][1] * bf_hi(ga.x)),
;                                pk2(acc[i][j][2] * bf_lo(ga.y), acc[i][j][3] * bf_hi(ga.y)));
;             }
;         }
	v_lshlrev_b32_e32 v40, 16, v234
	v_and_b32_e32 v41, 0xffff0000, v234
	v_lshlrev_b32_e32 v38, 16, v235
	v_and_b32_e32 v39, 0xffff0000, v235
	v_pk_mul_f32 v[34:35], v[34:35], v[40:41]
	v_pk_mul_f32 v[36:37], v[36:37], v[38:39]
	v_cvt_pk_bf16_f32 v34, v34, v35
	v_cvt_pk_bf16_f32 v35, v36, v37
	global_store_dwordx2 v[48:49], v[34:35], off offset:96
	global_load_dwordx2 v[228:229], v[76:77], off
	global_load_dwordx2 v[230:231], v[76:77], off offset:32
	global_load_dwordx2 v[232:233], v[76:77], off offset:64
	global_load_dwordx2 v[234:235], v[76:77], off offset:96
	s_waitcnt vmcnt(3)
	v_lshlrev_b32_e32 v36, 16, v228
	v_and_b32_e32 v37, 0xffff0000, v228
	v_lshlrev_b32_e32 v34, 16, v229
	v_and_b32_e32 v35, 0xffff0000, v229
	v_pk_mul_f32 v[30:31], v[30:31], v[36:37]
	v_pk_mul_f32 v[32:33], v[32:33], v[34:35]
	v_cvt_pk_bf16_f32 v30, v30, v31
	v_cvt_pk_bf16_f32 v31, v32, v33
	v_lshl_add_u64 v[32:33], v[78:79], 1, s[36:37]
	v_lshl_add_u64 v[32:33], v[32:33], 0, v[66:67]
	global_store_dwordx2 v[32:33], v[30:31], off
	s_waitcnt vmcnt(3)
	v_lshlrev_b32_e32 v34, 16, v230
	v_and_b32_e32 v35, 0xffff0000, v230
	v_lshlrev_b32_e32 v30, 16, v231
	v_and_b32_e32 v31, 0xffff0000, v231
	v_pk_mul_f32 v[26:27], v[26:27], v[34:35]
	v_pk_mul_f32 v[28:29], v[28:29], v[30:31]
	v_cvt_pk_bf16_f32 v26, v26, v27
	v_cvt_pk_bf16_f32 v27, v28, v29
	global_store_dwordx2 v[32:33], v[26:27], off offset:32
	s_waitcnt vmcnt(3)
	v_lshlrev_b32_e32 v28, 16, v232
	v_and_b32_e32 v29, 0xffff0000, v232
	v_lshlrev_b32_e32 v26, 16, v233
	v_and_b32_e32 v27, 0xffff0000, v233
	v_pk_mul_f32 v[22:23], v[22:23], v[28:29]
	v_pk_mul_f32 v[24:25], v[24:25], v[26:27]
	v_cvt_pk_bf16_f32 v22, v22, v23
	v_cvt_pk_bf16_f32 v23, v24, v25
	global_store_dwordx2 v[32:33], v[22:23], off offset:64
	s_waitcnt vmcnt(3)
	v_lshlrev_b32_e32 v24, 16, v234
	v_and_b32_e32 v25, 0xffff0000, v234
	v_lshlrev_b32_e32 v22, 16, v235
	v_and_b32_e32 v23, 0xffff0000, v235
	v_pk_mul_f32 v[18:19], v[18:19], v[24:25]
	v_pk_mul_f32 v[20:21], v[20:21], v[22:23]
	v_cvt_pk_bf16_f32 v18, v18, v19
	v_cvt_pk_bf16_f32 v19, v20, v21
	global_store_dwordx2 v[32:33], v[18:19], off offset:96
	global_load_dwordx2 v[228:229], v[80:81], off
	global_load_dwordx2 v[230:231], v[80:81], off offset:32
	global_load_dwordx2 v[232:233], v[80:81], off offset:64
	global_load_dwordx2 v[234:235], v[80:81], off offset:96
	s_waitcnt vmcnt(3)
	v_lshlrev_b32_e32 v20, 16, v228
	v_and_b32_e32 v21, 0xffff0000, v228
	v_lshlrev_b32_e32 v18, 16, v229
	v_and_b32_e32 v19, 0xffff0000, v229
	v_pk_mul_f32 v[14:15], v[14:15], v[20:21]
	v_pk_mul_f32 v[16:17], v[16:17], v[18:19]
	v_cvt_pk_bf16_f32 v14, v14, v15
	v_cvt_pk_bf16_f32 v15, v16, v17
	v_lshl_add_u64 v[16:17], v[82:83], 1, s[36:37]
	v_lshl_add_u64 v[16:17], v[16:17], 0, v[66:67]
	global_store_dwordx2 v[16:17], v[14:15], off
	v_readlane_b32 s36, v213, 38
	s_movk_i32 s37, 0x6ff
	s_waitcnt vmcnt(3)
	v_lshlrev_b32_e32 v18, 16, v230
	v_and_b32_e32 v19, 0xffff0000, v230
	v_lshlrev_b32_e32 v14, 16, v231
	v_and_b32_e32 v15, 0xffff0000, v231
	v_pk_mul_f32 v[10:11], v[10:11], v[18:19]
	v_pk_mul_f32 v[12:13], v[12:13], v[14:15]
	v_cvt_pk_bf16_f32 v10, v10, v11
	v_cvt_pk_bf16_f32 v11, v12, v13
	global_store_dwordx2 v[16:17], v[10:11], off offset:32
	s_waitcnt vmcnt(3)
	v_lshlrev_b32_e32 v12, 16, v232
	v_and_b32_e32 v13, 0xffff0000, v232
	v_lshlrev_b32_e32 v10, 16, v233
	v_and_b32_e32 v11, 0xffff0000, v233
	v_pk_mul_f32 v[6:7], v[6:7], v[12:13]
	v_pk_mul_f32 v[8:9], v[8:9], v[10:11]
	v_cvt_pk_bf16_f32 v6, v6, v7
	v_cvt_pk_bf16_f32 v7, v8, v9
	global_store_dwordx2 v[16:17], v[6:7], off offset:64
	s_waitcnt vmcnt(3)
	v_lshlrev_b32_e32 v8, 16, v234
	v_and_b32_e32 v9, 0xffff0000, v234
	v_lshlrev_b32_e32 v6, 16, v235
	v_and_b32_e32 v7, 0xffff0000, v235
	v_pk_mul_f32 v[2:3], v[2:3], v[8:9]
	v_pk_mul_f32 v[4:5], v[4:5], v[6:7]
	v_cvt_pk_bf16_f32 v2, v2, v3
	v_cvt_pk_bf16_f32 v3, v4, v5
	global_store_dwordx2 v[16:17], v[2:3], off offset:96
	s_branch .LBB0_698

; __device__ void phaseC2(const Params& p, int l, char* smem) {
;     ...
; #pragma unroll
;         for (int i = 0; i < 4; ++i) {
;             const size_t row = (size_t)(m0 + wr * 64 + i * 16 + r);
;             const float* xr;
;             if (l == 0) xr = (row < TP) ? (p.x_prompt + row * 1024) : (p.x_sample + (row - TP) * 1024);
;             else xr = p.out + O_Y + row * 1024;
; #pragma unroll
;             for (int j = 0; j < 4; ++j) {
;                 const int col = n0 + wc * 64 + j * 16 + g4 * 4;
;                 const float4 xv = *(const float4*)(xr + col);
;                 *(float4*)(p.preln + row * 1024 + col) =
;                     make_float4(fmaf(alpha, xv.x, acc[i][j][0]), fmaf(alpha, xv.y, acc[i][j][1]), fmaf(alpha, xv.z, acc[i][j][2]), fmaf(alpha, xv.w, acc[i][j][3]));
;             }
.LBB0_746:
	v_readlane_b32 s16, v213, 4
	v_readlane_b32 s28, v213, 16
	v_readlane_b32 s29, v213, 17
	v_lshl_add_u64 v[24:25], v[18:19], 0, v[68:69]
	s_mov_b32 s0, 0x3fb504f3
	v_lshl_add_u64 v[18:19], s[28:29], 0, v[22:23]
	v_lshl_add_u64 v[22:23], v[18:19], 0, v[68:69]
	global_load_dwordx4 v[228:231], v[24:25], off
	global_load_dwordx4 v[232:235], v[24:25], off offset:64
	global_load_dwordx4 v[236:239], v[24:25], off offset:128
	global_load_dwordx4 v[240:243], v[24:25], off offset:192
	v_readlane_b32 s17, v213, 5
	v_readlane_b32 s18, v213, 6
	v_readlane_b32 s19, v213, 7
	v_readlane_b32 s20, v213, 8
	v_readlane_b32 s21, v213, 9
	v_readlane_b32 s22, v213, 10
	v_readlane_b32 s23, v213, 11
	v_readlane_b32 s24, v213, 12
	v_readlane_b32 s25, v213, 13
	v_readlane_b32 s26, v213, 14
	v_readlane_b32 s27, v213, 15
	v_readlane_b32 s30, v213, 18
	v_readlane_b32 s31, v213, 19
	s_waitcnt vmcnt(3)
	v_pk_fma_f32 v[14:15], v[228:229], s[0:1], v[14:15] op_sel_hi:[1,0,1]
	v_pk_fma_f32 v[16:17], v[230:231], s[0:1], v[16:17] op_sel_hi:[1,0,1]
	global_store_dwordx4 v[22:23], v[14:17], off
	s_waitcnt vmcnt(3)
	v_pk_fma_f32 v[10:11], v[232:233], s[0:1], v[10:11] op_sel_hi:[1,0,1]
	v_pk_fma_f32 v[12:13], v[234:235], s[0:1], v[12:13] op_sel_hi:[1,0,1]
	global_store_dwordx4 v[22:23], v[10:13], off offset:64
	s_waitcnt vmcnt(3)
	v_pk_fma_f32 v[6:7], v[236:237], s[0:1], v[6:7] op_sel_hi:[1,0,1]
	v_pk_fma_f32 v[8:9], v[238:239], s[0:1], v[8:9] op_sel_hi:[1,0,1]
	global_store_dwordx4 v[22:23], v[6:9], off offset:128
	s_waitcnt vmcnt(3)
	v_pk_fma_f32 v[2:3], v[240:241], s[0:1], v[2:3] op_sel_hi:[1,0,1]
	v_pk_fma_f32 v[4:5], v[242:243], s[0:1], v[4:5] op_sel_hi:[1,0,1]
	global_store_dwordx4 v[22:23], v[2:5], off offset:192

; __device__ void phaseC2(const Params& p, int l, char* smem) {
;     ...
; #pragma unroll
;         for (int i = 0; i < 4; ++i) {
;             const size_t row = (size_t)(m0 + wr * 64 + i * 16 + r);
;             const float* xr;
;             if (l == 0) xr = (row < TP) ? (p.x_prompt + row * 1024) : (p.x_sample + (row - TP) * 1024);
;             else xr = p.out + O_Y + row * 1024;
; #pragma unroll
;             for (int j = 0; j < 4; ++j) {
;                 const int col = n0 + wc * 64 + j * 16 + g4 * 4;
;                 const float4 xv = *(const float4*)(xr + col);
;                 *(float4*)(p.preln + row * 1024 + col) =
;                     make_float4(fmaf(alpha, xv.x, acc[i][j][0]), fmaf(alpha, xv.y, acc[i][j][1]), fmaf(alpha, xv.z, acc[i][j][2]), fmaf(alpha, xv.w, acc[i][j][3]));
;             }
.LBB0_765:
	v_or_b32_e32 v68, s6, v76
	v_ashrrev_i32_e32 v69, 31, v68
	v_lshlrev_b64 v[68:69], 2, v[68:69]
	v_lshl_add_u64 v[72:73], v[72:73], 0, v[68:69]
	global_load_dwordx4 v[228:231], v[72:73], off
	global_load_dwordx4 v[232:235], v[72:73], off offset:64
	global_load_dwordx4 v[236:239], v[72:73], off offset:128
	global_load_dwordx4 v[240:243], v[72:73], off offset:192
	v_readlane_b32 s16, v213, 4
	v_readlane_b32 s28, v213, 16
	v_readlane_b32 s29, v213, 17
	s_mov_b32 s6, 0x3fb504f3
	s_andn2_b64 vcc, exec, s[74:75]
	v_lshl_add_u64 v[70:71], s[28:29], 0, v[70:71]
	v_lshl_add_u64 v[70:71], v[70:71], 0, v[68:69]
	v_readlane_b32 s17, v213, 5
	v_readlane_b32 s18, v213, 6
	v_readlane_b32 s19, v213, 7
	v_readlane_b32 s20, v213, 8
	v_readlane_b32 s21, v213, 9
	v_readlane_b32 s22, v213, 10
	v_readlane_b32 s23, v213, 11
	v_readlane_b32 s24, v213, 12
	v_readlane_b32 s25, v213, 13
	v_readlane_b32 s26, v213, 14
	v_readlane_b32 s27, v213, 15
	v_readlane_b32 s30, v213, 18
	v_readlane_b32 s31, v213, 19
	s_waitcnt vmcnt(3)
	v_pk_fma_f32 v[62:63], v[228:229], s[6:7], v[62:63] op_sel_hi:[1,0,1]
	v_pk_fma_f32 v[64:65], v[230:231], s[6:7], v[64:65] op_sel_hi:[1,0,1]
	global_store_dwordx4 v[70:71], v[62:65], off
	s_waitcnt vmcnt(3)
	v_pk_fma_f32 v[58:59], v[232:233], s[6:7], v[58:59] op_sel_hi:[1,0,1]
	v_pk_fma_f32 v[60:61], v[234:235], s[6:7], v[60:61] op_sel_hi:[1,0,1]
	global_store_dwordx4 v[70:71], v[58:61], off offset:64
	s_waitcnt vmcnt(3)
	v_pk_fma_f32 v[54:55], v[236:237], s[6:7], v[54:55] op_sel_hi:[1,0,1]
	v_pk_fma_f32 v[56:57], v[238:239], s[6:7], v[56:57] op_sel_hi:[1,0,1]
	global_store_dwordx4 v[70:71], v[54:57], off offset:128
	s_nop 1
	v_cndmask_b32_e64 v60, 0, 1, s[74:75]
	v_or_b32_e32 v54, 16, v66
	v_ashrrev_i32_e32 v55, 31, v54
	v_cmp_ne_u32_e64 s[0:1], 1, v60
	v_lshlrev_b64 v[54:55], 12, v[54:55]
	s_waitcnt vmcnt(3)
	v_pk_fma_f32 v[50:51], v[240:241], s[6:7], v[50:51] op_sel_hi:[1,0,1]
	v_pk_fma_f32 v[52:53], v[242:243], s[6:7], v[52:53] op_sel_hi:[1,0,1]
	s_mov_b64 s[6:7], -1
	global_store_dwordx4 v[70:71], v[50:53], off offset:192
	s_cbranch_vccnz .LBB0_767
	v_readlane_b32 s16, v214, 0
	v_readlane_b32 s26, v214, 10
	v_readlane_b32 s27, v214, 11
	s_mov_b64 s[6:7], 0
	v_readlane_b32 s17, v214, 1
	v_lshl_add_u64 v[50:51], s[26:27], 0, v[54:55]
	v_readlane_b32 s18, v214, 2
	v_readlane_b32 s19, v214, 3
	v_readlane_b32 s20, v214, 4
	v_readlane_b32 s21, v214, 5
	v_readlane_b32 s22, v214, 6
	v_readlane_b32 s23, v214, 7
	v_readlane_b32 s24, v214, 8
	v_readlane_b32 s25, v214, 9
	v_readlane_b32 s28, v214, 12
	v_readlane_b32 s29, v214, 13
	v_readlane_b32 s30, v214, 14
	v_readlane_b32 s31, v214, 15

; __device__ void phaseC2(const Params& p, int l, char* smem) {
;     ...
; #pragma unroll
;         for (int i = 0; i < 4; ++i) {
;             const size_t row = (size_t)(m0 + wr * 64 + i * 16 + r);
;             const float* xr;
;             if (l == 0) xr = (row < TP) ? (p.x_prompt + row * 1024) : (p.x_sample + (row - TP) * 1024);
;             else xr = p.out + O_Y + row * 1024;
; #pragma unroll
;             for (int j = 0; j < 4; ++j) {
;                 const int col = n0 + wc * 64 + j * 16 + g4 * 4;
;                 const float4 xv = *(const float4*)(xr + col);
;                 *(float4*)(p.preln + row * 1024 + col) =
;                     make_float4(fmaf(alpha, xv.x, acc[i][j][0]), fmaf(alpha, xv.y, acc[i][j][1]), fmaf(alpha, xv.z, acc[i][j][2]), fmaf(alpha, xv.w, acc[i][j][3]));
;             }
.LBB0_773:
	v_lshl_add_u64 v[56:57], v[50:51], 0, v[68:69]
	global_load_dwordx4 v[228:231], v[56:57], off
	global_load_dwordx4 v[232:235], v[56:57], off offset:64
	global_load_dwordx4 v[236:239], v[56:57], off offset:128
	global_load_dwordx4 v[240:243], v[56:57], off offset:192
	v_readlane_b32 s16, v213, 4
	v_readlane_b32 s28, v213, 16
	v_readlane_b32 s29, v213, 17
	s_mov_b32 s6, 0x3fb504f3
	s_and_b64 vcc, exec, s[0:1]
	v_lshl_add_u64 v[54:55], s[28:29], 0, v[54:55]
	v_lshl_add_u64 v[54:55], v[54:55], 0, v[68:69]
	v_readlane_b32 s17, v213, 5
	v_readlane_b32 s18, v213, 6
	v_readlane_b32 s19, v213, 7
	v_readlane_b32 s20, v213, 8
	v_readlane_b32 s21, v213, 9
	v_readlane_b32 s22, v213, 10
	v_readlane_b32 s23, v213, 11
	v_readlane_b32 s24, v213, 12
	v_readlane_b32 s25, v213, 13
	v_readlane_b32 s26, v213, 14
	v_readlane_b32 s27, v213, 15
	v_readlane_b32 s30, v213, 18
	v_readlane_b32 s31, v213, 19
	s_waitcnt vmcnt(3)
	v_pk_fma_f32 v[46:47], v[228:229], s[6:7], v[46:47] op_sel_hi:[1,0,1]
	v_pk_fma_f32 v[48:49], v[230:231], s[6:7], v[48:49] op_sel_hi:[1,0,1]
	global_store_dwordx4 v[54:55], v[46:49], off
	s_waitcnt vmcnt(3)
	v_pk_fma_f32 v[42:43], v[232:233], s[6:7], v[42:43] op_sel_hi:[1,0,1]
	v_pk_fma_f32 v[44:45], v[234:235], s[6:7], v[44:45] op_sel_hi:[1,0,1]
	global_store_dwordx4 v[54:55], v[42:45], off offset:64
	s_waitcnt vmcnt(3)
	v_pk_fma_f32 v[38:39], v[236:237], s[6:7], v[38:39] op_sel_hi:[1,0,1]
	v_pk_fma_f32 v[40:41], v[238:239], s[6:7], v[40:41] op_sel_hi:[1,0,1]
	global_store_dwordx4 v[54:55], v[38:41], off offset:128
	s_waitcnt vmcnt(3)
	v_pk_fma_f32 v[34:35], v[240:241], s[6:7], v[34:35] op_sel_hi:[1,0,1]
	v_or_b32_e32 v38, 32, v66
	v_ashrrev_i32_e32 v39, 31, v38
	v_lshlrev_b64 v[38:39], 12, v[38:39]
	v_pk_fma_f32 v[36:37], v[242:243], s[6:7], v[36:37] op_sel_hi:[1,0,1]
	s_mov_b64 s[6:7], -1
	global_store_dwordx4 v[54:55], v[34:37], off offset:192
	s_cbranch_vccnz .LBB0_775
	v_readlane_b32 s16, v214, 0
	v_readlane_b32 s26, v214, 10
	v_readlane_b32 s27, v214, 11
	s_mov_b64 s[6:7], 0
	v_readlane_b32 s17, v214, 1
	v_lshl_add_u64 v[34:35], s[26:27], 0, v[38:39]
	v_readlane_b32 s18, v214, 2
	v_readlane_b32 s19, v214, 3
	v_readlane_b32 s20, v214, 4
	v_readlane_b32 s21, v214, 5
	v_readlane_b32 s22, v214, 6
	v_readlane_b32 s23, v214, 7
	v_readlane_b32 s24, v214, 8
	v_readlane_b32 s25, v214, 9
	v_readlane_b32 s28, v214, 12
	v_readlane_b32 s29, v214, 13
	v_readlane_b32 s30, v214, 14
	v_readlane_b32 s31, v214, 15

; __device__ void phaseC2(const Params& p, int l, char* smem) {
;     ...
; #pragma unroll
;         for (int i = 0; i < 4; ++i) {
;             const size_t row = (size_t)(m0 + wr * 64 + i * 16 + r);
;             const float* xr;
;             if (l == 0) xr = (row < TP) ? (p.x_prompt + row * 1024) : (p.x_sample + (row - TP) * 1024);
;             else xr = p.out + O_Y + row * 1024;
; #pragma unroll
;             for (int j = 0; j < 4; ++j) {
;                 const int col = n0 + wc * 64 + j * 16 + g4 * 4;
;                 const float4 xv = *(const float4*)(xr + col);
;                 *(float4*)(p.preln + row * 1024 + col) =
;                     make_float4(fmaf(alpha, xv.x, acc[i][j][0]), fmaf(alpha, xv.y, acc[i][j][1]), fmaf(alpha, xv.z, acc[i][j][2]), fmaf(alpha, xv.w, acc[i][j][3]));
;             }
.LBB0_781:
	v_lshl_add_u64 v[40:41], v[34:35], 0, v[68:69]
	global_load_dwordx4 v[228:231], v[40:41], off
	global_load_dwordx4 v[232:235], v[40:41], off offset:64
	global_load_dwordx4 v[236:239], v[40:41], off offset:128
	global_load_dwordx4 v[240:243], v[40:41], off offset:192
	v_readlane_b32 s16, v213, 4
	v_readlane_b32 s28, v213, 16
	v_readlane_b32 s29, v213, 17
	s_mov_b32 s6, 0x3fb504f3
	s_and_b64 vcc, exec, s[0:1]
	v_lshl_add_u64 v[38:39], s[28:29], 0, v[38:39]
	v_lshl_add_u64 v[38:39], v[38:39], 0, v[68:69]
	s_mov_b64 s[0:1], -1
	v_readlane_b32 s17, v213, 5
	v_readlane_b32 s18, v213, 6
	v_readlane_b32 s19, v213, 7
	v_readlane_b32 s20, v213, 8
	v_readlane_b32 s21, v213, 9
	v_readlane_b32 s22, v213, 10
	v_readlane_b32 s23, v213, 11
	v_readlane_b32 s24, v213, 12
	v_readlane_b32 s25, v213, 13
	v_readlane_b32 s26, v213, 14
	v_readlane_b32 s27, v213, 15
	v_readlane_b32 s30, v213, 18
	v_readlane_b32 s31, v213, 19
	s_waitcnt vmcnt(3)
	v_pk_fma_f32 v[30:31], v[228:229], s[6:7], v[30:31] op_sel_hi:[1,0,1]
	v_pk_fma_f32 v[32:33], v[230:231], s[6:7], v[32:33] op_sel_hi:[1,0,1]
	global_store_dwordx4 v[38:39], v[30:33], off
	s_waitcnt vmcnt(3)
	v_pk_fma_f32 v[26:27], v[232:233], s[6:7], v[26:27] op_sel_hi:[1,0,1]
	v_pk_fma_f32 v[28:29], v[234:235], s[6:7], v[28:29] op_sel_hi:[1,0,1]
	global_store_dwordx4 v[38:39], v[26:29], off offset:64
	s_waitcnt vmcnt(3)
	v_pk_fma_f32 v[22:23], v[236:237], s[6:7], v[22:23] op_sel_hi:[1,0,1]
	v_pk_fma_f32 v[24:25], v[238:239], s[6:7], v[24:25] op_sel_hi:[1,0,1]
	global_store_dwordx4 v[38:39], v[22:25], off offset:128
	s_waitcnt vmcnt(3)
	v_pk_fma_f32 v[18:19], v[240:241], s[6:7], v[18:19] op_sel_hi:[1,0,1]
	v_or_b32_e32 v22, 48, v66
	v_ashrrev_i32_e32 v23, 31, v22
	v_lshlrev_b64 v[22:23], 12, v[22:23]
	v_pk_fma_f32 v[20:21], v[242:243], s[6:7], v[20:21] op_sel_hi:[1,0,1]
	global_store_dwordx4 v[38:39], v[18:21], off offset:192
	s_cbranch_vccnz .LBB0_783
	v_readlane_b32 s16, v214, 0
	v_readlane_b32 s26, v214, 10
	v_readlane_b32 s27, v214, 11
	s_mov_b64 s[0:1], 0
	v_readlane_b32 s17, v214, 1
	v_lshl_add_u64 v[18:19], s[26:27], 0, v[22:23]
	v_readlane_b32 s18, v214, 2
	v_readlane_b32 s19, v214, 3
	v_readlane_b32 s20, v214, 4
	v_readlane_b32 s21, v214, 5
	v_readlane_b32 s22, v214, 6
	v_readlane_b32 s23, v214, 7
	v_readlane_b32 s24, v214, 8
	v_readlane_b32 s25, v214, 9
	v_readlane_b32 s28, v214, 12
	v_readlane_b32 s29, v214, 13
	v_readlane_b32 s30, v214, 14
	v_readlane_b32 s31, v214, 15
